# GEMM K loops: m0 write hoisted above the address add so the s_nop before each LDS-DMA load goes (10 instructions fewer per iteration)
# speedup vs baseline: 1.0143x; 1.0043x over previous
.LBB0_118:
	ds_read_b128 v[128:131], v221
	ds_read_b128 v[132:135], v221 offset:1024
	ds_read_b128 v[136:139], v221 offset:2048
	ds_read_b128 v[140:143], v221 offset:3072
	s_add_u32 s8, s6, 0xfff80080
	s_addc_u32 s9, s7, -1
	s_cmp_eq_u32 s53, 28
	s_cselect_b32 s11, s5, s9
	s_cselect_b32 s10, s33, s8
	s_cselect_b32 s9, s43, s52
	s_cselect_b32 s8, s45, s51
	v_lshl_add_u64 v[198:199], s[6:7], 0, v[182:183]
	s_add_i32 m0, s58, 0xc000
	ds_read_b128 v[144:147], v222
	ds_read_b128 v[148:151], v222 offset:1024
	ds_read_b128 v[152:155], v222 offset:2048
	ds_read_b128 v[156:159], v222 offset:3072
	ds_read_b128 v[160:163], v222 offset:4096
	ds_read_b128 v[164:167], v222 offset:5120
	ds_read_b128 v[190:193], v222 offset:6144
	ds_read_b128 v[194:197], v222 offset:7168
	global_load_lds_dwordx4 v[198:199], off
	s_add_i32 m0, s58, 0xe000
	v_lshl_add_u64 v[198:199], s[6:7], 0, v[184:185]

	global_load_lds_dwordx4 v[198:199], off
	s_waitcnt lgkmcnt(8)
	s_barrier
	s_waitcnt lgkmcnt(0)


	v_mfma_f32_16x16x32_bf16 v[124:127], v[128:131], v[144:147], v[124:127]
	v_mfma_f32_16x16x32_bf16 v[116:119], v[136:139], v[144:147], v[116:119]
	v_mfma_f32_16x16x32_bf16 v[108:111], v[128:131], v[152:155], v[108:111]
	v_mfma_f32_16x16x32_bf16 v[100:103], v[136:139], v[152:155], v[100:103]
	v_mfma_f32_16x16x32_bf16 v[92:95], v[128:131], v[160:163], v[92:95]
	v_mfma_f32_16x16x32_bf16 v[84:87], v[136:139], v[160:163], v[84:87]
	v_mfma_f32_16x16x32_bf16 v[76:79], v[128:131], v[190:193], v[76:79]
	v_mfma_f32_16x16x32_bf16 v[68:71], v[136:139], v[190:193], v[68:71]
	v_mfma_f32_16x16x32_bf16 v[124:127], v[132:135], v[148:151], v[124:127]
	v_mfma_f32_16x16x32_bf16 v[116:119], v[140:143], v[148:151], v[116:119]
	v_mfma_f32_16x16x32_bf16 v[108:111], v[132:135], v[156:159], v[108:111]
	v_mfma_f32_16x16x32_bf16 v[100:103], v[140:143], v[156:159], v[100:103]
	v_mfma_f32_16x16x32_bf16 v[92:95], v[132:135], v[164:167], v[92:95]
	v_mfma_f32_16x16x32_bf16 v[84:87], v[140:143], v[164:167], v[84:87]
	v_mfma_f32_16x16x32_bf16 v[76:79], v[132:135], v[194:197], v[76:79]
	v_mfma_f32_16x16x32_bf16 v[68:71], v[140:143], v[194:197], v[68:71]

	s_barrier
	s_add_i32 s54, s81, s57
	v_lshl_add_u64 v[230:231], s[8:9], 0, v[172:173]
	s_mov_b32 m0, s54
	ds_read_b128 v[198:201], v223
	ds_read_b128 v[202:205], v223 offset:1024
	ds_read_b128 v[206:209], v223 offset:2048
	ds_read_b128 v[226:229], v223 offset:3072
	global_load_lds_dwordx4 v[230:231], off
	s_add_i32 m0, s54, 0x2000
	v_lshl_add_u64 v[232:233], s[8:9], 0, v[174:175]

	global_load_lds_dwordx4 v[232:233], off
	s_barrier
	s_waitcnt lgkmcnt(0)


	v_mfma_f32_16x16x32_bf16 v[120:123], v[198:201], v[144:147], v[120:123]
	v_mfma_f32_16x16x32_bf16 v[112:115], v[206:209], v[144:147], v[112:115]
	v_mfma_f32_16x16x32_bf16 v[104:107], v[198:201], v[152:155], v[104:107]
	v_mfma_f32_16x16x32_bf16 v[96:99], v[206:209], v[152:155], v[96:99]
	v_mfma_f32_16x16x32_bf16 v[88:91], v[198:201], v[160:163], v[88:91]
	v_mfma_f32_16x16x32_bf16 v[80:83], v[206:209], v[160:163], v[80:83]
	v_mfma_f32_16x16x32_bf16 v[72:75], v[198:201], v[190:193], v[72:75]
	v_mfma_f32_16x16x32_bf16 v[64:67], v[206:209], v[190:193], v[64:67]
	v_mfma_f32_16x16x32_bf16 v[120:123], v[202:205], v[148:151], v[120:123]
	v_mfma_f32_16x16x32_bf16 v[112:115], v[226:229], v[148:151], v[112:115]
	v_mfma_f32_16x16x32_bf16 v[104:107], v[202:205], v[156:159], v[104:107]
	v_mfma_f32_16x16x32_bf16 v[96:99], v[226:229], v[156:159], v[96:99]
	v_mfma_f32_16x16x32_bf16 v[88:91], v[202:205], v[164:167], v[88:91]
	v_mfma_f32_16x16x32_bf16 v[80:83], v[226:229], v[164:167], v[80:83]
	v_mfma_f32_16x16x32_bf16 v[72:75], v[202:205], v[194:197], v[72:75]
	v_mfma_f32_16x16x32_bf16 v[64:67], v[226:229], v[194:197], v[64:67]

	s_mov_b32 m0, s58
	v_lshl_add_u64 v[234:235], s[10:11], 0, v[172:173]
	s_barrier
	ds_read_b128 v[144:147], v222 offset:16384
	ds_read_b128 v[148:151], v222 offset:17408
	ds_read_b128 v[152:155], v222 offset:18432
	ds_read_b128 v[156:159], v222 offset:19456
	ds_read_b128 v[160:163], v222 offset:20480
	ds_read_b128 v[164:167], v222 offset:21504
	ds_read_b128 v[190:193], v222 offset:22528
	ds_read_b128 v[194:197], v222 offset:23552
	global_load_lds_dwordx4 v[234:235], off
	s_mov_b32 m0, s59
	v_lshl_add_u64 v[236:237], s[10:11], 0, v[174:175]

	global_load_lds_dwordx4 v[236:237], off
	s_barrier
	s_waitcnt lgkmcnt(0)


	v_mfma_f32_16x16x32_bf16 v[60:63], v[128:131], v[144:147], v[60:63]
	v_mfma_f32_16x16x32_bf16 v[52:55], v[136:139], v[144:147], v[52:55]
	v_mfma_f32_16x16x32_bf16 v[44:47], v[128:131], v[152:155], v[44:47]
	v_mfma_f32_16x16x32_bf16 v[36:39], v[136:139], v[152:155], v[36:39]
	v_mfma_f32_16x16x32_bf16 v[28:31], v[128:131], v[160:163], v[28:31]
	v_mfma_f32_16x16x32_bf16 v[20:23], v[136:139], v[160:163], v[20:23]
	v_mfma_f32_16x16x32_bf16 v[12:15], v[128:131], v[190:193], v[12:15]
	v_mfma_f32_16x16x32_bf16 v[4:7], v[136:139], v[190:193], v[4:7]
	v_mfma_f32_16x16x32_bf16 v[60:63], v[132:135], v[148:151], v[60:63]
	v_mfma_f32_16x16x32_bf16 v[52:55], v[140:143], v[148:151], v[52:55]
	v_mfma_f32_16x16x32_bf16 v[44:47], v[132:135], v[156:159], v[44:47]
	v_mfma_f32_16x16x32_bf16 v[36:39], v[140:143], v[156:159], v[36:39]
	v_mfma_f32_16x16x32_bf16 v[28:31], v[132:135], v[164:167], v[28:31]
	v_mfma_f32_16x16x32_bf16 v[20:23], v[140:143], v[164:167], v[20:23]
	v_mfma_f32_16x16x32_bf16 v[12:15], v[132:135], v[194:197], v[12:15]
	v_mfma_f32_16x16x32_bf16 v[4:7], v[140:143], v[194:197], v[4:7]

	s_barrier
	s_add_u32 s54, s8, 0x80000
	s_addc_u32 s55, s9, 0
	s_add_i32 vcc_lo, s30, s57
	s_mov_b32 m0, vcc_lo
	v_lshl_add_u64 v[128:129], s[54:55], 0, v[172:173]

	global_load_lds_dwordx4 v[128:129], off
	s_add_i32 m0, vcc_lo, 0x2000
	v_lshl_add_u64 v[128:129], s[54:55], 0, v[174:175]

	global_load_lds_dwordx4 v[128:129], off
	s_waitcnt vmcnt(6)
	s_barrier

	v_mfma_f32_16x16x32_bf16 v[56:59], v[198:201], v[144:147], v[56:59]
	v_mfma_f32_16x16x32_bf16 v[48:51], v[206:209], v[144:147], v[48:51]
	v_mfma_f32_16x16x32_bf16 v[40:43], v[198:201], v[152:155], v[40:43]
	v_mfma_f32_16x16x32_bf16 v[32:35], v[206:209], v[152:155], v[32:35]
	v_mfma_f32_16x16x32_bf16 v[24:27], v[198:201], v[160:163], v[24:27]
	v_mfma_f32_16x16x32_bf16 v[16:19], v[206:209], v[160:163], v[16:19]
	v_mfma_f32_16x16x32_bf16 v[8:11], v[198:201], v[190:193], v[8:11]
	v_mfma_f32_16x16x32_bf16 v[0:3], v[206:209], v[190:193], v[0:3]
	v_mfma_f32_16x16x32_bf16 v[56:59], v[202:205], v[148:151], v[56:59]
	v_mfma_f32_16x16x32_bf16 v[48:51], v[226:229], v[148:151], v[48:51]
	v_mfma_f32_16x16x32_bf16 v[40:43], v[202:205], v[156:159], v[40:43]
	v_mfma_f32_16x16x32_bf16 v[32:35], v[226:229], v[156:159], v[32:35]
	v_mfma_f32_16x16x32_bf16 v[24:27], v[202:205], v[164:167], v[24:27]
	v_mfma_f32_16x16x32_bf16 v[16:19], v[226:229], v[164:167], v[16:19]
	v_mfma_f32_16x16x32_bf16 v[8:11], v[202:205], v[194:197], v[8:11]
	v_mfma_f32_16x16x32_bf16 v[0:3], v[226:229], v[194:197], v[0:3]

	s_add_i32 s54, 0, 0x18000
	v_add_u32_e32 v140, s54, v179
	s_barrier
	ds_read_b128 v[128:131], v140
	ds_read_b128 v[132:135], v140 offset:1024
	ds_read_b128 v[136:139], v140 offset:2048
	ds_read_b128 v[140:143], v140 offset:3072
	s_add_u32 s10, s10, 0x80000
	s_addc_u32 s11, s11, 0
	s_mov_b32 m0, s2
	v_lshl_add_u64 v[198:199], s[10:11], 0, v[172:173]
	ds_read_b128 v[144:147], v222 offset:32768
	ds_read_b128 v[148:151], v222 offset:33792
	ds_read_b128 v[152:155], v222 offset:34816
	ds_read_b128 v[156:159], v222 offset:35840
	ds_read_b128 v[160:163], v222 offset:36864
	ds_read_b128 v[164:167], v222 offset:37888
	ds_read_b128 v[190:193], v222 offset:38912
	ds_read_b128 v[194:197], v222 offset:39936
	global_load_lds_dwordx4 v[198:199], off
	s_mov_b32 m0, s3
	v_lshl_add_u64 v[198:199], s[10:11], 0, v[174:175]

	global_load_lds_dwordx4 v[198:199], off
	s_waitcnt lgkmcnt(8)
	s_barrier
	s_waitcnt lgkmcnt(0)


	v_mfma_f32_16x16x32_bf16 v[124:127], v[128:131], v[144:147], v[124:127]
	v_mfma_f32_16x16x32_bf16 v[116:119], v[136:139], v[144:147], v[116:119]
	v_mfma_f32_16x16x32_bf16 v[108:111], v[128:131], v[152:155], v[108:111]
	v_mfma_f32_16x16x32_bf16 v[100:103], v[136:139], v[152:155], v[100:103]
	v_mfma_f32_16x16x32_bf16 v[92:95], v[128:131], v[160:163], v[92:95]
	v_mfma_f32_16x16x32_bf16 v[84:87], v[136:139], v[160:163], v[84:87]
	v_mfma_f32_16x16x32_bf16 v[76:79], v[128:131], v[190:193], v[76:79]
	v_mfma_f32_16x16x32_bf16 v[68:71], v[136:139], v[190:193], v[68:71]
	v_mfma_f32_16x16x32_bf16 v[124:127], v[132:135], v[148:151], v[124:127]
	v_mfma_f32_16x16x32_bf16 v[116:119], v[140:143], v[148:151], v[116:119]
	v_mfma_f32_16x16x32_bf16 v[108:111], v[132:135], v[156:159], v[108:111]
	v_mfma_f32_16x16x32_bf16 v[100:103], v[140:143], v[156:159], v[100:103]
	v_mfma_f32_16x16x32_bf16 v[92:95], v[132:135], v[164:167], v[92:95]
	v_mfma_f32_16x16x32_bf16 v[84:87], v[140:143], v[164:167], v[84:87]
	v_mfma_f32_16x16x32_bf16 v[76:79], v[132:135], v[194:197], v[76:79]
	v_mfma_f32_16x16x32_bf16 v[68:71], v[140:143], v[194:197], v[68:71]

	s_barrier
	s_add_i32 s10, 0, 0x1c000
	s_add_i32 s11, s54, s57
	v_add_u32_e32 v180, s10, v179
	v_lshl_add_u64 v[230:231], v[230:231], 0, s[20:21]
	s_mov_b32 m0, s11
	ds_read_b128 v[198:201], v180
	ds_read_b128 v[202:205], v180 offset:1024
	ds_read_b128 v[206:209], v180 offset:2048
	ds_read_b128 v[226:229], v180 offset:3072
	global_load_lds_dwordx4 v[230:231], off
	s_add_i32 m0, s11, 0x2000
	v_lshl_add_u64 v[230:231], v[232:233], 0, s[20:21]

	global_load_lds_dwordx4 v[230:231], off
	s_barrier
	s_waitcnt lgkmcnt(0)


	v_mfma_f32_16x16x32_bf16 v[120:123], v[198:201], v[144:147], v[120:123]
	v_mfma_f32_16x16x32_bf16 v[112:115], v[206:209], v[144:147], v[112:115]
	v_mfma_f32_16x16x32_bf16 v[104:107], v[198:201], v[152:155], v[104:107]
	v_mfma_f32_16x16x32_bf16 v[96:99], v[206:209], v[152:155], v[96:99]
	v_mfma_f32_16x16x32_bf16 v[88:91], v[198:201], v[160:163], v[88:91]
	v_mfma_f32_16x16x32_bf16 v[80:83], v[206:209], v[160:163], v[80:83]
	v_mfma_f32_16x16x32_bf16 v[72:75], v[198:201], v[190:193], v[72:75]
	v_mfma_f32_16x16x32_bf16 v[64:67], v[206:209], v[190:193], v[64:67]
	v_mfma_f32_16x16x32_bf16 v[120:123], v[202:205], v[148:151], v[120:123]
	v_mfma_f32_16x16x32_bf16 v[112:115], v[226:229], v[148:151], v[112:115]
	v_mfma_f32_16x16x32_bf16 v[104:107], v[202:205], v[156:159], v[104:107]
	v_mfma_f32_16x16x32_bf16 v[96:99], v[226:229], v[156:159], v[96:99]
	v_mfma_f32_16x16x32_bf16 v[88:91], v[202:205], v[164:167], v[88:91]
	v_mfma_f32_16x16x32_bf16 v[80:83], v[226:229], v[164:167], v[80:83]
	v_mfma_f32_16x16x32_bf16 v[72:75], v[202:205], v[194:197], v[72:75]
	v_mfma_f32_16x16x32_bf16 v[64:67], v[226:229], v[194:197], v[64:67]

	s_mov_b32 m0, s96
	v_lshl_add_u64 v[230:231], v[234:235], 0, s[20:21]
	s_barrier
	ds_read_b128 v[144:147], v222 offset:49152
	ds_read_b128 v[148:151], v222 offset:50176
	ds_read_b128 v[152:155], v222 offset:51200
	ds_read_b128 v[156:159], v222 offset:52224
	ds_read_b128 v[160:163], v222 offset:53248
	ds_read_b128 v[164:167], v222 offset:54272
	ds_read_b128 v[190:193], v222 offset:55296
	ds_read_b128 v[194:197], v222 offset:56320
	global_load_lds_dwordx4 v[230:231], off
	s_mov_b32 m0, s97
	v_lshl_add_u64 v[230:231], v[236:237], 0, s[20:21]

	global_load_lds_dwordx4 v[230:231], off
	s_barrier
	s_waitcnt lgkmcnt(0)


	v_mfma_f32_16x16x32_bf16 v[60:63], v[128:131], v[144:147], v[60:63]
	v_mfma_f32_16x16x32_bf16 v[52:55], v[136:139], v[144:147], v[52:55]
	v_mfma_f32_16x16x32_bf16 v[44:47], v[128:131], v[152:155], v[44:47]
	v_mfma_f32_16x16x32_bf16 v[36:39], v[136:139], v[152:155], v[36:39]
	v_mfma_f32_16x16x32_bf16 v[28:31], v[128:131], v[160:163], v[28:31]
	v_mfma_f32_16x16x32_bf16 v[20:23], v[136:139], v[160:163], v[20:23]
	v_mfma_f32_16x16x32_bf16 v[12:15], v[128:131], v[190:193], v[12:15]
	v_mfma_f32_16x16x32_bf16 v[4:7], v[136:139], v[190:193], v[4:7]
	v_mfma_f32_16x16x32_bf16 v[60:63], v[132:135], v[148:151], v[60:63]
	v_mfma_f32_16x16x32_bf16 v[52:55], v[140:143], v[148:151], v[52:55]
	v_mfma_f32_16x16x32_bf16 v[44:47], v[132:135], v[156:159], v[44:47]
	v_mfma_f32_16x16x32_bf16 v[36:39], v[140:143], v[156:159], v[36:39]
	v_mfma_f32_16x16x32_bf16 v[28:31], v[132:135], v[164:167], v[28:31]
	v_mfma_f32_16x16x32_bf16 v[20:23], v[140:143], v[164:167], v[20:23]
	v_mfma_f32_16x16x32_bf16 v[12:15], v[132:135], v[194:197], v[12:15]
	v_mfma_f32_16x16x32_bf16 v[4:7], v[140:143], v[194:197], v[4:7]

	s_barrier
	s_add_u32 s8, s8, 0x80080
	s_addc_u32 s9, s9, 0
	s_add_i32 s10, s10, s57
	s_mov_b32 m0, s10
	v_lshl_add_u64 v[128:129], s[8:9], 0, v[172:173]

	global_load_lds_dwordx4 v[128:129], off
	s_add_i32 m0, s10, 0x2000
	v_lshl_add_u64 v[128:129], s[8:9], 0, v[174:175]

	global_load_lds_dwordx4 v[128:129], off
	s_waitcnt vmcnt(6)
	s_barrier

	v_mfma_f32_16x16x32_bf16 v[56:59], v[198:201], v[144:147], v[56:59]
	v_mfma_f32_16x16x32_bf16 v[48:51], v[206:209], v[144:147], v[48:51]
	v_mfma_f32_16x16x32_bf16 v[40:43], v[198:201], v[152:155], v[40:43]
	v_mfma_f32_16x16x32_bf16 v[32:35], v[206:209], v[152:155], v[32:35]
	v_mfma_f32_16x16x32_bf16 v[24:27], v[198:201], v[160:163], v[24:27]
	v_mfma_f32_16x16x32_bf16 v[16:19], v[206:209], v[160:163], v[16:19]
	v_mfma_f32_16x16x32_bf16 v[8:11], v[198:201], v[190:193], v[8:11]
	v_mfma_f32_16x16x32_bf16 v[0:3], v[206:209], v[190:193], v[0:3]
	v_mfma_f32_16x16x32_bf16 v[56:59], v[202:205], v[148:151], v[56:59]
	v_mfma_f32_16x16x32_bf16 v[48:51], v[226:229], v[148:151], v[48:51]
	v_mfma_f32_16x16x32_bf16 v[40:43], v[202:205], v[156:159], v[40:43]
	v_mfma_f32_16x16x32_bf16 v[32:35], v[226:229], v[156:159], v[32:35]
	v_mfma_f32_16x16x32_bf16 v[24:27], v[202:205], v[164:167], v[24:27]
	v_mfma_f32_16x16x32_bf16 v[16:19], v[226:229], v[164:167], v[16:19]
	v_mfma_f32_16x16x32_bf16 v[8:11], v[202:205], v[194:197], v[8:11]
	v_mfma_f32_16x16x32_bf16 v[0:3], v[226:229], v[194:197], v[0:3]

	s_add_i32 s53, s53, 2
	s_add_u32 s6, s6, 0x100
	s_addc_u32 s7, s7, 0
	s_add_u32 s51, s51, 0x100
	s_addc_u32 s52, s52, 0
	s_cmp_gt_u32 s53, 29
	s_barrier
	s_cbranch_scc0 .LBB0_118
	v_mov_b32_e32 v142, v210
	v_mov_b32_e32 v143, v169
	s_lshl_b32 s33, s4, 8
	s_add_i32 s33, s33, s34
	v_lshl_add_u32 v133, v142, 4, v143
	v_ashrrev_i32_e32 v198, 2, v133
	v_and_b32_e32 v192, 3, v143
	v_and_b32_e32 v128, -4, v133
	s_cmp_gt_i32 s4, 30
	v_lshl_add_u32 v226, v192, 6, v128
	v_add_u32_e32 v190, s33, v198
	s_cselect_b64 s[52:53], -1, 0
	s_cmp_gt_i32 s50, 8
	s_mov_b64 s[4:5], -1
	s_cbranch_scc0 .LBB0_419
	s_cmp_lg_u32 s50, 9
	s_cbranch_scc0 .LBB0_225
	s_cmp_gt_u32 s50, 25
	s_cbranch_scc0 .LBB0_127
	v_mul_f32_e32 v130, 0xbfb8aa3b, v120
	v_mul_f32_e32 v131, 0xbfb8aa3b, v121
	v_mul_f32_e32 v132, 0xbfb8aa3b, v122
	v_mul_f32_e32 v134, 0xbfb8aa3b, v123
	v_mul_f32_e32 v135, 0xbfb8aa3b, v112
	v_mul_f32_e32 v136, 0xbfb8aa3b, v113
	v_mul_f32_e32 v137, 0xbfb8aa3b, v114
	v_mul_f32_e32 v138, 0xbfb8aa3b, v115
	v_mul_f32_e32 v139, 0xbfb8aa3b, v104
	v_mul_f32_e32 v140, 0xbfb8aa3b, v105
	v_mul_f32_e32 v141, 0xbfb8aa3b, v106
	v_mul_f32_e32 v144, 0xbfb8aa3b, v107
	v_mul_f32_e32 v145, 0xbfb8aa3b, v96
	v_mul_f32_e32 v146, 0xbfb8aa3b, v97
	v_mul_f32_e32 v147, 0xbfb8aa3b, v98
	v_mul_f32_e32 v148, 0xbfb8aa3b, v99
	v_mul_f32_e32 v149, 0xbfb8aa3b, v88
	v_mul_f32_e32 v150, 0xbfb8aa3b, v89
	v_mul_f32_e32 v151, 0xbfb8aa3b, v90
	v_mul_f32_e32 v152, 0xbfb8aa3b, v91
	v_mul_f32_e32 v153, 0xbfb8aa3b, v80
	v_mul_f32_e32 v154, 0xbfb8aa3b, v81
	v_mul_f32_e32 v155, 0xbfb8aa3b, v82
	v_mul_f32_e32 v180, 0xbfb8aa3b, v83
	v_mul_f32_e32 v206, 0xbfb8aa3b, v72
	v_mul_f32_e32 v207, 0xbfb8aa3b, v73
	v_mul_f32_e32 v208, 0xbfb8aa3b, v74
	v_mul_f32_e32 v209, 0xbfb8aa3b, v75
	v_mul_f32_e32 v227, 0xbfb8aa3b, v64
	v_mul_f32_e32 v228, 0xbfb8aa3b, v65
	v_mul_f32_e32 v229, 0xbfb8aa3b, v66
	v_mul_f32_e32 v230, 0xbfb8aa3b, v67
	v_exp_f32_e32 v205, v130
	v_exp_f32_e32 v204, v131
	v_exp_f32_e32 v203, v132
	v_exp_f32_e32 v202, v134
	v_exp_f32_e32 v200, v135
	v_exp_f32_e32 v199, v136
	v_exp_f32_e32 v197, v137
	v_exp_f32_e32 v196, v138
	v_exp_f32_e32 v195, v139
	v_exp_f32_e32 v194, v140
	v_exp_f32_e32 v193, v141
	v_exp_f32_e32 v167, v144
	v_exp_f32_e32 v166, v145
	v_exp_f32_e32 v165, v146
	v_exp_f32_e32 v164, v147
	v_exp_f32_e32 v163, v148
	v_exp_f32_e32 v162, v149
	v_exp_f32_e32 v161, v150
	v_exp_f32_e32 v160, v151
	v_exp_f32_e32 v159, v152
	v_exp_f32_e32 v158, v153
	v_exp_f32_e32 v157, v154
	v_exp_f32_e32 v156, v155
	v_exp_f32_e32 v155, v180
	v_exp_f32_e32 v154, v206
	v_exp_f32_e32 v153, v207
	v_exp_f32_e32 v152, v208
	v_exp_f32_e32 v151, v209
	v_exp_f32_e32 v150, v227
	v_exp_f32_e32 v149, v228
	v_exp_f32_e32 v148, v229
	v_exp_f32_e32 v147, v230
	v_ashrrev_i32_e32 v191, 31, v190
	s_cmp_lt_u32 s50, 42
	v_lshlrev_b32_e32 v201, 2, v192
	v_lshlrev_b64 v[128:129], 12, v[190:191]
	v_mul_f32_e32 v146, 0xbfb8aa3b, v56
	v_mul_f32_e32 v145, 0xbfb8aa3b, v57
	v_mul_f32_e32 v144, 0xbfb8aa3b, v58
	v_mul_f32_e32 v141, 0xbfb8aa3b, v59
	v_mul_f32_e32 v140, 0xbfb8aa3b, v48
	v_mul_f32_e32 v139, 0xbfb8aa3b, v49
	v_mul_f32_e32 v138, 0xbfb8aa3b, v50
	v_mul_f32_e32 v137, 0xbfb8aa3b, v51
	v_mul_f32_e32 v136, 0xbfb8aa3b, v40
	v_mul_f32_e32 v135, 0xbfb8aa3b, v41
	v_mul_f32_e32 v134, 0xbfb8aa3b, v42
	v_mul_f32_e32 v132, 0xbfb8aa3b, v43
	s_cbranch_scc1 .LBB0_124
	v_mul_f32_e32 v130, 0xbfb8aa3b, v124
	v_mul_f32_e32 v131, 0xbfb8aa3b, v125
	v_mul_f32_e32 v206, 0xbfb8aa3b, v126
	v_mul_f32_e32 v207, 0xbfb8aa3b, v127
	v_exp_f32_e32 v130, v130
	v_exp_f32_e32 v131, v131
	v_exp_f32_e32 v206, v206
	v_exp_f32_e32 v207, v207
	v_add_f32_e32 v130, 1.0, v130
	v_add_f32_e32 v131, 1.0, v131
	v_add_f32_e32 v206, 1.0, v206
	v_add_f32_e32 v207, 1.0, v207
	v_rcp_f32_e32 v130, v130
	v_rcp_f32_e32 v131, v131
	v_rcp_f32_e32 v206, v206
	v_rcp_f32_e32 v207, v207
	s_lshl_b32 s4, s50, 8
	v_cvt_pk_bf16_f32 v130, v130, v131
	s_add_i32 s4, s28, s4
	v_cvt_pk_bf16_f32 v131, v206, v207
	ds_bpermute_b32 v206, v226, v130
	ds_bpermute_b32 v207, v226, v131
	v_or_b32_e32 v180, s4, v201
	v_lshl_add_u64 v[130:131], s[40:41], 0, v[128:129]
	v_lshlrev_b64 v[208:209], 1, v[180:181]
	v_lshl_add_u64 v[130:131], v[130:131], 0, v[208:209]
	s_waitcnt lgkmcnt(0)
	global_store_dwordx2 v[130:131], v[206:207], off
	v_mul_f32_e32 v180, 0xbfb8aa3b, v116
	v_mul_f32_e32 v206, 0xbfb8aa3b, v117
	v_mul_f32_e32 v207, 0xbfb8aa3b, v118
	v_mul_f32_e32 v208, 0xbfb8aa3b, v119
	v_exp_f32_e32 v180, v180
	v_exp_f32_e32 v206, v206
	v_exp_f32_e32 v207, v207
	v_exp_f32_e32 v208, v208
	v_add_f32_e32 v180, 1.0, v180
	v_add_f32_e32 v206, 1.0, v206
	v_add_f32_e32 v207, 1.0, v207
	v_add_f32_e32 v208, 1.0, v208
	v_rcp_f32_e32 v180, v180
	v_rcp_f32_e32 v206, v206
	v_rcp_f32_e32 v207, v207
	v_rcp_f32_e32 v208, v208
	s_mov_b64 s[4:5], 0x10000
	v_cvt_pk_bf16_f32 v180, v180, v206
	ds_bpermute_b32 v206, v226, v180
	v_cvt_pk_bf16_f32 v207, v207, v208
	ds_bpermute_b32 v207, v226, v207
	v_add_f32_e32 v180, 1.0, v205
	v_add_f32_e32 v208, 1.0, v202
	v_rcp_f32_e32 v180, v180
	v_rcp_f32_e32 v208, v208
	s_waitcnt lgkmcnt(0)
	global_store_dwordx2 v[130:131], v[206:207], off offset:32
	v_add_f32_e32 v206, 1.0, v204
	v_add_f32_e32 v207, 1.0, v203
	v_rcp_f32_e32 v206, v206
	v_rcp_f32_e32 v207, v207
	v_mul_f32_e32 v227, 0xbfb8aa3b, v103
	v_exp_f32_e32 v227, v227
	v_cvt_pk_bf16_f32 v180, v180, v206
	v_cvt_pk_bf16_f32 v207, v207, v208
	ds_bpermute_b32 v206, v226, v180
	ds_bpermute_b32 v207, v226, v207
	v_add_f32_e32 v180, 1.0, v200
	v_add_f32_e32 v208, 1.0, v196
	v_rcp_f32_e32 v180, v180
	v_rcp_f32_e32 v208, v208
	s_waitcnt lgkmcnt(0)
	global_store_dwordx2 v[130:131], v[206:207], off offset:256
	v_add_f32_e32 v206, 1.0, v199
	v_add_f32_e32 v207, 1.0, v197
	v_rcp_f32_e32 v206, v206
	v_rcp_f32_e32 v207, v207
	v_add_f32_e32 v227, 1.0, v227
	v_rcp_f32_e32 v227, v227
	v_cvt_pk_bf16_f32 v180, v180, v206
	v_cvt_pk_bf16_f32 v207, v207, v208
	ds_bpermute_b32 v206, v226, v180
	ds_bpermute_b32 v207, v226, v207
	v_mul_f32_e32 v180, 0xbfb8aa3b, v108
	v_mul_f32_e32 v208, 0xbfb8aa3b, v111
	v_exp_f32_e32 v180, v180
	v_exp_f32_e32 v208, v208
	s_waitcnt lgkmcnt(0)
	global_store_dwordx2 v[130:131], v[206:207], off offset:288
	v_mul_f32_e32 v206, 0xbfb8aa3b, v109
	v_mul_f32_e32 v207, 0xbfb8aa3b, v110
	v_exp_f32_e32 v206, v206
	v_exp_f32_e32 v207, v207
	v_add_f32_e32 v180, 1.0, v180
	v_add_f32_e32 v208, 1.0, v208
	v_add_f32_e32 v206, 1.0, v206
	v_add_f32_e32 v207, 1.0, v207
	v_rcp_f32_e32 v180, v180
	v_rcp_f32_e32 v206, v206
	v_rcp_f32_e32 v207, v207
	v_rcp_f32_e32 v208, v208
	v_cvt_pk_bf16_f32 v180, v180, v206
	ds_bpermute_b32 v206, v226, v180
	v_cvt_pk_bf16_f32 v207, v207, v208
	ds_bpermute_b32 v207, v226, v207
	v_lshl_add_u64 v[208:209], v[130:131], 0, s[4:5]
	s_mov_b32 s4, 0x10000
	v_add_co_u32_e32 v228, vcc, s4, v130
	v_mul_f32_e32 v180, 0xbfb8aa3b, v100
	s_nop 0
	v_addc_co_u32_e32 v229, vcc, 0, v131, vcc
	s_waitcnt lgkmcnt(0)
	global_store_dwordx2 v[228:229], v[206:207], off
	v_mul_f32_e32 v206, 0xbfb8aa3b, v101
	v_mul_f32_e32 v207, 0xbfb8aa3b, v102
	v_exp_f32_e32 v180, v180
	v_exp_f32_e32 v206, v206
	v_exp_f32_e32 v207, v207
	s_mov_b64 s[4:5], 0x20000
	v_add_f32_e32 v180, 1.0, v180
	v_add_f32_e32 v206, 1.0, v206
	v_add_f32_e32 v207, 1.0, v207
	v_rcp_f32_e32 v180, v180
	v_rcp_f32_e32 v206, v206
	v_rcp_f32_e32 v207, v207
	v_cvt_pk_bf16_f32 v180, v180, v206
	v_cvt_pk_bf16_f32 v207, v207, v227
	ds_bpermute_b32 v206, v226, v180
	ds_bpermute_b32 v207, v226, v207
	v_add_f32_e32 v180, 1.0, v195
	v_add_f32_e32 v227, 1.0, v167
	v_rcp_f32_e32 v180, v180
	v_rcp_f32_e32 v227, v227
	s_waitcnt lgkmcnt(0)
	global_store_dwordx2 v[208:209], v[206:207], off offset:32
	v_add_f32_e32 v206, 1.0, v194
	v_add_f32_e32 v207, 1.0, v193
	v_rcp_f32_e32 v206, v206
	v_rcp_f32_e32 v207, v207
	v_cvt_pk_bf16_f32 v180, v180, v206
	v_cvt_pk_bf16_f32 v207, v207, v227
	ds_bpermute_b32 v206, v226, v180
	ds_bpermute_b32 v207, v226, v207
	v_add_f32_e32 v180, 1.0, v166
	v_add_f32_e32 v227, 1.0, v163
	v_rcp_f32_e32 v180, v180
	v_rcp_f32_e32 v227, v227
	s_waitcnt lgkmcnt(0)
	global_store_dwordx2 v[208:209], v[206:207], off offset:256
	v_add_f32_e32 v206, 1.0, v165
	v_add_f32_e32 v207, 1.0, v164
	v_rcp_f32_e32 v206, v206
	v_rcp_f32_e32 v207, v207
	v_cvt_pk_bf16_f32 v180, v180, v206
	v_cvt_pk_bf16_f32 v207, v207, v227
	ds_bpermute_b32 v206, v226, v180
	ds_bpermute_b32 v207, v226, v207
	v_mul_f32_e32 v180, 0xbfb8aa3b, v92
	v_exp_f32_e32 v180, v180
	v_mul_f32_e32 v227, 0xbfb8aa3b, v87
	v_exp_f32_e32 v227, v227
	s_waitcnt lgkmcnt(0)
	global_store_dwordx2 v[208:209], v[206:207], off offset:288
	v_mul_f32_e32 v206, 0xbfb8aa3b, v93
	v_mul_f32_e32 v207, 0xbfb8aa3b, v94
	v_mul_f32_e32 v208, 0xbfb8aa3b, v95
	v_exp_f32_e32 v206, v206
	v_exp_f32_e32 v207, v207
	v_exp_f32_e32 v208, v208
	v_add_f32_e32 v180, 1.0, v180
	v_add_f32_e32 v206, 1.0, v206
	v_add_f32_e32 v207, 1.0, v207
	v_add_f32_e32 v208, 1.0, v208
	v_rcp_f32_e32 v180, v180
	v_rcp_f32_e32 v206, v206
	v_rcp_f32_e32 v207, v207
	v_rcp_f32_e32 v208, v208
	v_add_f32_e32 v227, 1.0, v227
	v_cvt_pk_bf16_f32 v180, v180, v206
	ds_bpermute_b32 v206, v226, v180
	v_cvt_pk_bf16_f32 v207, v207, v208
	ds_bpermute_b32 v207, v226, v207
	v_lshl_add_u64 v[208:209], v[130:131], 0, s[4:5]
	s_mov_b32 s4, 0x20000
	v_add_co_u32_e32 v228, vcc, s4, v130
	v_mul_f32_e32 v180, 0xbfb8aa3b, v84
	s_nop 0
	v_addc_co_u32_e32 v229, vcc, 0, v131, vcc
	s_waitcnt lgkmcnt(0)
	global_store_dwordx2 v[228:229], v[206:207], off
	v_mul_f32_e32 v206, 0xbfb8aa3b, v85
	v_mul_f32_e32 v207, 0xbfb8aa3b, v86
	v_exp_f32_e32 v180, v180
	v_exp_f32_e32 v206, v206
	v_exp_f32_e32 v207, v207
	v_rcp_f32_e32 v227, v227
	v_add_f32_e32 v180, 1.0, v180
	v_add_f32_e32 v206, 1.0, v206
	v_add_f32_e32 v207, 1.0, v207
	v_rcp_f32_e32 v180, v180
	v_rcp_f32_e32 v206, v206
	v_rcp_f32_e32 v207, v207
	s_mov_b64 s[4:5], 0x30000
	v_cvt_pk_bf16_f32 v180, v180, v206
	v_cvt_pk_bf16_f32 v207, v207, v227
	ds_bpermute_b32 v206, v226, v180
	ds_bpermute_b32 v207, v226, v207
	v_add_f32_e32 v180, 1.0, v162
	v_add_f32_e32 v227, 1.0, v159
	v_rcp_f32_e32 v180, v180
	v_rcp_f32_e32 v227, v227
	s_waitcnt lgkmcnt(0)
	global_store_dwordx2 v[208:209], v[206:207], off offset:32
	v_add_f32_e32 v206, 1.0, v161
	v_add_f32_e32 v207, 1.0, v160
	v_rcp_f32_e32 v206, v206
	v_rcp_f32_e32 v207, v207
	v_cvt_pk_bf16_f32 v180, v180, v206
	v_cvt_pk_bf16_f32 v207, v207, v227
	ds_bpermute_b32 v206, v226, v180
	ds_bpermute_b32 v207, v226, v207
	v_add_f32_e32 v180, 1.0, v158
	v_add_f32_e32 v227, 1.0, v155
	v_rcp_f32_e32 v180, v180
	v_rcp_f32_e32 v227, v227
	s_waitcnt lgkmcnt(0)
	global_store_dwordx2 v[208:209], v[206:207], off offset:256
	v_add_f32_e32 v206, 1.0, v157
	v_add_f32_e32 v207, 1.0, v156
	v_rcp_f32_e32 v206, v206
	v_rcp_f32_e32 v207, v207
	v_cvt_pk_bf16_f32 v180, v180, v206
	v_cvt_pk_bf16_f32 v207, v207, v227
	ds_bpermute_b32 v206, v226, v180
	ds_bpermute_b32 v207, v226, v207
	v_mul_f32_e32 v180, 0xbfb8aa3b, v76
	v_exp_f32_e32 v180, v180
	v_mul_f32_e32 v227, 0xbfb8aa3b, v71
	v_exp_f32_e32 v227, v227
	s_waitcnt lgkmcnt(0)
	global_store_dwordx2 v[208:209], v[206:207], off offset:288
	v_mul_f32_e32 v206, 0xbfb8aa3b, v77
	v_mul_f32_e32 v207, 0xbfb8aa3b, v78
	v_mul_f32_e32 v208, 0xbfb8aa3b, v79
	v_exp_f32_e32 v206, v206
	v_exp_f32_e32 v207, v207
	v_exp_f32_e32 v208, v208
	v_add_f32_e32 v180, 1.0, v180
	v_add_f32_e32 v206, 1.0, v206
	v_add_f32_e32 v207, 1.0, v207
	v_add_f32_e32 v208, 1.0, v208
	v_rcp_f32_e32 v180, v180
	v_rcp_f32_e32 v206, v206
	v_rcp_f32_e32 v207, v207
	v_rcp_f32_e32 v208, v208
	v_add_f32_e32 v227, 1.0, v227
	v_cvt_pk_bf16_f32 v180, v180, v206
	ds_bpermute_b32 v206, v226, v180
	v_cvt_pk_bf16_f32 v207, v207, v208
	ds_bpermute_b32 v207, v226, v207
	v_lshl_add_u64 v[208:209], v[130:131], 0, s[4:5]
	s_mov_b32 s4, 0x30000
	v_add_co_u32_e32 v228, vcc, s4, v130
	v_mul_f32_e32 v180, 0xbfb8aa3b, v68
	s_nop 0
	v_addc_co_u32_e32 v229, vcc, 0, v131, vcc
	s_waitcnt lgkmcnt(0)
	global_store_dwordx2 v[228:229], v[206:207], off
	v_mul_f32_e32 v206, 0xbfb8aa3b, v69
	v_mul_f32_e32 v207, 0xbfb8aa3b, v70
	v_exp_f32_e32 v180, v180
	v_exp_f32_e32 v206, v206
	v_exp_f32_e32 v207, v207
	v_rcp_f32_e32 v227, v227
	v_add_f32_e32 v180, 1.0, v180
	v_add_f32_e32 v206, 1.0, v206
	v_add_f32_e32 v207, 1.0, v207
	v_rcp_f32_e32 v180, v180
	v_rcp_f32_e32 v206, v206
	v_rcp_f32_e32 v207, v207
	s_mov_b64 s[4:5], 0x80000
	v_cvt_pk_bf16_f32 v180, v180, v206
	v_cvt_pk_bf16_f32 v207, v207, v227
	ds_bpermute_b32 v206, v226, v180
	ds_bpermute_b32 v207, v226, v207
	v_add_f32_e32 v180, 1.0, v154
	v_add_f32_e32 v227, 1.0, v151
	v_rcp_f32_e32 v180, v180
	v_rcp_f32_e32 v227, v227
	s_waitcnt lgkmcnt(0)
	global_store_dwordx2 v[208:209], v[206:207], off offset:32
	v_add_f32_e32 v206, 1.0, v153
	v_add_f32_e32 v207, 1.0, v152
	v_rcp_f32_e32 v206, v206
	v_rcp_f32_e32 v207, v207
	v_cvt_pk_bf16_f32 v180, v180, v206
	v_cvt_pk_bf16_f32 v207, v207, v227
	ds_bpermute_b32 v206, v226, v180
	ds_bpermute_b32 v207, v226, v207
	v_add_f32_e32 v180, 1.0, v150
	v_add_f32_e32 v227, 1.0, v147
	v_rcp_f32_e32 v180, v180
	v_rcp_f32_e32 v227, v227
	s_waitcnt lgkmcnt(0)
	global_store_dwordx2 v[208:209], v[206:207], off offset:256
	v_add_f32_e32 v206, 1.0, v149
	v_add_f32_e32 v207, 1.0, v148
	v_rcp_f32_e32 v206, v206
	v_rcp_f32_e32 v207, v207
	v_cvt_pk_bf16_f32 v180, v180, v206
	v_cvt_pk_bf16_f32 v207, v207, v227
	ds_bpermute_b32 v206, v226, v180
	ds_bpermute_b32 v207, v226, v207
	v_mul_f32_e32 v180, 0xbfb8aa3b, v60
	v_exp_f32_e32 v180, v180
	v_mul_f32_e32 v227, 0xbfb8aa3b, v55
	v_exp_f32_e32 v227, v227
	s_waitcnt lgkmcnt(0)
	global_store_dwordx2 v[208:209], v[206:207], off offset:288
	v_mul_f32_e32 v206, 0xbfb8aa3b, v61
	v_mul_f32_e32 v207, 0xbfb8aa3b, v62
	v_mul_f32_e32 v208, 0xbfb8aa3b, v63
	v_exp_f32_e32 v206, v206
	v_exp_f32_e32 v207, v207
	v_exp_f32_e32 v208, v208
	v_add_f32_e32 v180, 1.0, v180
	v_add_f32_e32 v206, 1.0, v206
	v_add_f32_e32 v207, 1.0, v207
	v_add_f32_e32 v208, 1.0, v208
	v_rcp_f32_e32 v180, v180
	v_rcp_f32_e32 v206, v206
	v_rcp_f32_e32 v207, v207
	v_rcp_f32_e32 v208, v208
	v_add_f32_e32 v227, 1.0, v227
	v_cvt_pk_bf16_f32 v180, v180, v206
	ds_bpermute_b32 v206, v226, v180
	v_cvt_pk_bf16_f32 v207, v207, v208
	ds_bpermute_b32 v207, v226, v207
	v_lshl_add_u64 v[208:209], v[130:131], 0, s[4:5]
	s_mov_b32 s4, 0x80000
	v_add_co_u32_e32 v228, vcc, s4, v130
	v_mul_f32_e32 v180, 0xbfb8aa3b, v52
	s_nop 0
	v_addc_co_u32_e32 v229, vcc, 0, v131, vcc
	s_waitcnt lgkmcnt(0)
	global_store_dwordx2 v[228:229], v[206:207], off
	v_mul_f32_e32 v206, 0xbfb8aa3b, v53
	v_mul_f32_e32 v207, 0xbfb8aa3b, v54
	v_exp_f32_e32 v180, v180
	v_exp_f32_e32 v206, v206
	v_exp_f32_e32 v207, v207
	v_rcp_f32_e32 v227, v227
	v_add_f32_e32 v180, 1.0, v180
	v_add_f32_e32 v206, 1.0, v206
	v_add_f32_e32 v207, 1.0, v207
	v_rcp_f32_e32 v180, v180
	v_rcp_f32_e32 v206, v206
	v_rcp_f32_e32 v207, v207
	s_mov_b64 s[4:5], 0x90000
	v_cvt_pk_bf16_f32 v180, v180, v206
	v_cvt_pk_bf16_f32 v207, v207, v227
	ds_bpermute_b32 v206, v226, v180
	ds_bpermute_b32 v207, v226, v207
	v_exp_f32_e32 v180, v146
	v_exp_f32_e32 v227, v141
	s_waitcnt lgkmcnt(0)
	global_store_dwordx2 v[208:209], v[206:207], off offset:32
	v_exp_f32_e32 v206, v145
	v_exp_f32_e32 v207, v144
	v_add_f32_e32 v180, 1.0, v180
	v_add_f32_e32 v227, 1.0, v227
	v_add_f32_e32 v206, 1.0, v206
	v_add_f32_e32 v207, 1.0, v207
	v_rcp_f32_e32 v180, v180
	v_rcp_f32_e32 v206, v206
	v_rcp_f32_e32 v207, v207
	v_rcp_f32_e32 v227, v227
	v_cvt_pk_bf16_f32 v180, v180, v206
	ds_bpermute_b32 v206, v226, v180
	v_cvt_pk_bf16_f32 v207, v207, v227
	ds_bpermute_b32 v207, v226, v207
	v_exp_f32_e32 v180, v140
	v_exp_f32_e32 v227, v137
	s_waitcnt lgkmcnt(0)
	global_store_dwordx2 v[208:209], v[206:207], off offset:256
	v_exp_f32_e32 v206, v139
	v_exp_f32_e32 v207, v138
	v_add_f32_e32 v180, 1.0, v180
	v_add_f32_e32 v227, 1.0, v227
	v_add_f32_e32 v206, 1.0, v206
	v_add_f32_e32 v207, 1.0, v207
	v_rcp_f32_e32 v180, v180
	v_rcp_f32_e32 v206, v206
	v_rcp_f32_e32 v207, v207
	v_rcp_f32_e32 v227, v227
	v_cvt_pk_bf16_f32 v180, v180, v206
	ds_bpermute_b32 v206, v226, v180
	v_cvt_pk_bf16_f32 v207, v207, v227
	ds_bpermute_b32 v207, v226, v207
	v_mul_f32_e32 v180, 0xbfb8aa3b, v44
	v_exp_f32_e32 v180, v180
	v_mul_f32_e32 v227, 0xbfb8aa3b, v39
	v_exp_f32_e32 v227, v227
	s_waitcnt lgkmcnt(0)
	global_store_dwordx2 v[208:209], v[206:207], off offset:288
	v_mul_f32_e32 v206, 0xbfb8aa3b, v45
	v_mul_f32_e32 v207, 0xbfb8aa3b, v46
	v_mul_f32_e32 v208, 0xbfb8aa3b, v47
	v_exp_f32_e32 v206, v206
	v_exp_f32_e32 v207, v207
	v_exp_f32_e32 v208, v208
	v_add_f32_e32 v180, 1.0, v180
	v_add_f32_e32 v206, 1.0, v206
	v_add_f32_e32 v207, 1.0, v207
	v_add_f32_e32 v208, 1.0, v208
	v_rcp_f32_e32 v180, v180
	v_rcp_f32_e32 v206, v206
	v_rcp_f32_e32 v207, v207
	v_rcp_f32_e32 v208, v208
	v_add_f32_e32 v227, 1.0, v227
	v_cvt_pk_bf16_f32 v180, v180, v206
	ds_bpermute_b32 v206, v226, v180
	v_cvt_pk_bf16_f32 v207, v207, v208
	ds_bpermute_b32 v207, v226, v207
	v_lshl_add_u64 v[208:209], v[130:131], 0, s[4:5]
	s_mov_b32 s4, 0x90000
	v_add_co_u32_e32 v228, vcc, s4, v130
	v_mul_f32_e32 v180, 0xbfb8aa3b, v36
	s_nop 0
	v_addc_co_u32_e32 v229, vcc, 0, v131, vcc
	s_waitcnt lgkmcnt(0)
	global_store_dwordx2 v[228:229], v[206:207], off
	v_mul_f32_e32 v206, 0xbfb8aa3b, v37
	v_mul_f32_e32 v207, 0xbfb8aa3b, v38
	v_exp_f32_e32 v180, v180
	v_exp_f32_e32 v206, v206
	v_exp_f32_e32 v207, v207
	v_rcp_f32_e32 v227, v227
	v_add_f32_e32 v180, 1.0, v180
	v_add_f32_e32 v206, 1.0, v206
	v_add_f32_e32 v207, 1.0, v207
	v_rcp_f32_e32 v180, v180
	v_rcp_f32_e32 v206, v206
	v_rcp_f32_e32 v207, v207
	s_mov_b64 s[4:5], 0xa0000
	v_cvt_pk_bf16_f32 v180, v180, v206
	v_cvt_pk_bf16_f32 v207, v207, v227
	ds_bpermute_b32 v206, v226, v180
	ds_bpermute_b32 v207, v226, v207
	v_exp_f32_e32 v180, v136
	v_exp_f32_e32 v227, v132
	s_waitcnt lgkmcnt(0)
	global_store_dwordx2 v[208:209], v[206:207], off offset:32
	v_exp_f32_e32 v206, v135
	v_exp_f32_e32 v207, v134
	v_add_f32_e32 v180, 1.0, v180
	v_add_f32_e32 v227, 1.0, v227
	v_add_f32_e32 v206, 1.0, v206
	v_add_f32_e32 v207, 1.0, v207
	v_rcp_f32_e32 v180, v180
	v_rcp_f32_e32 v206, v206
	v_rcp_f32_e32 v207, v207
	v_rcp_f32_e32 v227, v227
	v_cvt_pk_bf16_f32 v180, v180, v206
	ds_bpermute_b32 v206, v226, v180
	v_cvt_pk_bf16_f32 v207, v207, v227
	ds_bpermute_b32 v207, v226, v207
	v_mul_f32_e32 v180, 0xbfb8aa3b, v32
	v_mul_f32_e32 v227, 0xbfb8aa3b, v35
	v_exp_f32_e32 v180, v180
	v_exp_f32_e32 v227, v227
	s_waitcnt lgkmcnt(0)
	global_store_dwordx2 v[208:209], v[206:207], off offset:256
	v_mul_f32_e32 v206, 0xbfb8aa3b, v33
	v_mul_f32_e32 v207, 0xbfb8aa3b, v34
	v_exp_f32_e32 v206, v206
	v_exp_f32_e32 v207, v207
	v_add_f32_e32 v180, 1.0, v180
	v_add_f32_e32 v227, 1.0, v227
	v_add_f32_e32 v206, 1.0, v206
	v_add_f32_e32 v207, 1.0, v207
	v_rcp_f32_e32 v180, v180
	v_rcp_f32_e32 v206, v206
	v_rcp_f32_e32 v207, v207
	v_rcp_f32_e32 v227, v227
	v_cvt_pk_bf16_f32 v180, v180, v206
	ds_bpermute_b32 v206, v226, v180
	v_cvt_pk_bf16_f32 v207, v207, v227
	ds_bpermute_b32 v207, v226, v207
	v_mul_f32_e32 v180, 0xbfb8aa3b, v28
	v_exp_f32_e32 v180, v180
	v_mul_f32_e32 v227, 0xbfb8aa3b, v23
	v_exp_f32_e32 v227, v227
	s_waitcnt lgkmcnt(0)
	global_store_dwordx2 v[208:209], v[206:207], off offset:288
	v_mul_f32_e32 v206, 0xbfb8aa3b, v29
	v_mul_f32_e32 v207, 0xbfb8aa3b, v30
	v_mul_f32_e32 v208, 0xbfb8aa3b, v31
	v_exp_f32_e32 v206, v206
	v_exp_f32_e32 v207, v207
	v_exp_f32_e32 v208, v208
	v_add_f32_e32 v180, 1.0, v180
	v_add_f32_e32 v206, 1.0, v206
	v_add_f32_e32 v207, 1.0, v207
	v_add_f32_e32 v208, 1.0, v208
	v_rcp_f32_e32 v180, v180
	v_rcp_f32_e32 v206, v206
	v_rcp_f32_e32 v207, v207
	v_rcp_f32_e32 v208, v208
	v_add_f32_e32 v227, 1.0, v227
	v_cvt_pk_bf16_f32 v180, v180, v206
	ds_bpermute_b32 v206, v226, v180
	v_cvt_pk_bf16_f32 v207, v207, v208
	ds_bpermute_b32 v207, v226, v207
	v_lshl_add_u64 v[208:209], v[130:131], 0, s[4:5]
	s_mov_b32 s4, 0xa0000
	v_add_co_u32_e32 v228, vcc, s4, v130
	v_mul_f32_e32 v180, 0xbfb8aa3b, v20
	s_nop 0
	v_addc_co_u32_e32 v229, vcc, 0, v131, vcc
	s_waitcnt lgkmcnt(0)
	global_store_dwordx2 v[228:229], v[206:207], off
	v_mul_f32_e32 v206, 0xbfb8aa3b, v21
	v_mul_f32_e32 v207, 0xbfb8aa3b, v22
	v_exp_f32_e32 v180, v180
	v_exp_f32_e32 v206, v206
	v_exp_f32_e32 v207, v207
	v_rcp_f32_e32 v227, v227
	v_add_f32_e32 v180, 1.0, v180
	v_add_f32_e32 v206, 1.0, v206
	v_add_f32_e32 v207, 1.0, v207
	v_rcp_f32_e32 v180, v180
	v_rcp_f32_e32 v206, v206
	v_rcp_f32_e32 v207, v207
	s_mov_b64 s[4:5], 0xb0000
	v_cvt_pk_bf16_f32 v180, v180, v206
	v_cvt_pk_bf16_f32 v207, v207, v227
	ds_bpermute_b32 v206, v226, v180
	ds_bpermute_b32 v207, v226, v207
	v_mul_f32_e32 v180, 0xbfb8aa3b, v24
	v_mul_f32_e32 v227, 0xbfb8aa3b, v27
	v_exp_f32_e32 v180, v180
	v_exp_f32_e32 v227, v227
	s_waitcnt lgkmcnt(0)
	global_store_dwordx2 v[208:209], v[206:207], off offset:32
	v_mul_f32_e32 v206, 0xbfb8aa3b, v25
	v_mul_f32_e32 v207, 0xbfb8aa3b, v26
	v_exp_f32_e32 v206, v206
	v_exp_f32_e32 v207, v207
	v_add_f32_e32 v180, 1.0, v180
	v_add_f32_e32 v227, 1.0, v227
	v_add_f32_e32 v206, 1.0, v206
	v_add_f32_e32 v207, 1.0, v207
	v_rcp_f32_e32 v180, v180
	v_rcp_f32_e32 v206, v206
	v_rcp_f32_e32 v207, v207
	v_rcp_f32_e32 v227, v227
	v_cvt_pk_bf16_f32 v180, v180, v206
	ds_bpermute_b32 v206, v226, v180
	v_cvt_pk_bf16_f32 v207, v207, v227
	ds_bpermute_b32 v207, v226, v207
	v_mul_f32_e32 v180, 0xbfb8aa3b, v16
	v_mul_f32_e32 v227, 0xbfb8aa3b, v19
	v_exp_f32_e32 v180, v180
	v_exp_f32_e32 v227, v227
	s_waitcnt lgkmcnt(0)
	global_store_dwordx2 v[208:209], v[206:207], off offset:256
	v_mul_f32_e32 v206, 0xbfb8aa3b, v17
	v_mul_f32_e32 v207, 0xbfb8aa3b, v18
	v_exp_f32_e32 v206, v206
	v_exp_f32_e32 v207, v207
	v_add_f32_e32 v180, 1.0, v180
	v_add_f32_e32 v227, 1.0, v227
	v_add_f32_e32 v206, 1.0, v206
	v_add_f32_e32 v207, 1.0, v207
	v_rcp_f32_e32 v180, v180
	v_rcp_f32_e32 v206, v206
	v_rcp_f32_e32 v207, v207
	v_rcp_f32_e32 v227, v227
	v_cvt_pk_bf16_f32 v180, v180, v206
	ds_bpermute_b32 v206, v226, v180
	v_cvt_pk_bf16_f32 v207, v207, v227
	ds_bpermute_b32 v207, v226, v207
	v_mul_f32_e32 v180, 0xbfb8aa3b, v12
	v_exp_f32_e32 v180, v180
	s_waitcnt lgkmcnt(0)
	global_store_dwordx2 v[208:209], v[206:207], off offset:288
	v_mul_f32_e32 v206, 0xbfb8aa3b, v13
	v_mul_f32_e32 v207, 0xbfb8aa3b, v14
	v_mul_f32_e32 v208, 0xbfb8aa3b, v15
	v_exp_f32_e32 v206, v206
	v_exp_f32_e32 v207, v207
	v_exp_f32_e32 v208, v208
	v_add_f32_e32 v180, 1.0, v180
	v_add_f32_e32 v206, 1.0, v206
	v_add_f32_e32 v207, 1.0, v207
	v_add_f32_e32 v208, 1.0, v208
	v_rcp_f32_e32 v180, v180
	v_rcp_f32_e32 v206, v206
	v_rcp_f32_e32 v207, v207
	v_rcp_f32_e32 v208, v208
	v_cvt_pk_bf16_f32 v180, v180, v206
	ds_bpermute_b32 v206, v226, v180
	v_cvt_pk_bf16_f32 v207, v207, v208
	ds_bpermute_b32 v207, v226, v207
	v_lshl_add_u64 v[208:209], v[130:131], 0, s[4:5]
	s_mov_b32 s4, 0xb0000
	v_add_co_u32_e32 v130, vcc, s4, v130
	v_mul_f32_e32 v180, 0xbfb8aa3b, v6
	s_nop 0
	v_addc_co_u32_e32 v131, vcc, 0, v131, vcc
	s_waitcnt lgkmcnt(0)
	global_store_dwordx2 v[130:131], v[206:207], off
	v_mul_f32_e32 v130, 0xbfb8aa3b, v4
	v_mul_f32_e32 v131, 0xbfb8aa3b, v5
	v_mul_f32_e32 v206, 0xbfb8aa3b, v7
	v_exp_f32_e32 v130, v130
	v_exp_f32_e32 v131, v131
	v_exp_f32_e32 v180, v180
	v_exp_f32_e32 v206, v206
	v_add_f32_e32 v130, 1.0, v130
	v_add_f32_e32 v131, 1.0, v131
	v_add_f32_e32 v180, 1.0, v180
	v_add_f32_e32 v206, 1.0, v206
	v_rcp_f32_e32 v130, v130
	v_rcp_f32_e32 v131, v131
	v_rcp_f32_e32 v180, v180
	v_rcp_f32_e32 v206, v206
	s_mov_b64 s[4:5], 0
	v_cvt_pk_bf16_f32 v130, v130, v131
	ds_bpermute_b32 v130, v226, v130
	v_cvt_pk_bf16_f32 v131, v180, v206
	ds_bpermute_b32 v131, v226, v131
	v_mul_f32_e32 v180, 0xbfb8aa3b, v10
	v_mul_f32_e32 v206, 0xbfb8aa3b, v11
	v_exp_f32_e32 v180, v180
	v_exp_f32_e32 v206, v206
	s_waitcnt lgkmcnt(0)
	global_store_dwordx2 v[208:209], v[130:131], off offset:32
	v_mul_f32_e32 v130, 0xbfb8aa3b, v8
	v_mul_f32_e32 v131, 0xbfb8aa3b, v9
	v_exp_f32_e32 v130, v130
	v_exp_f32_e32 v131, v131
	v_add_f32_e32 v180, 1.0, v180
	v_add_f32_e32 v206, 1.0, v206
	v_add_f32_e32 v130, 1.0, v130
	v_add_f32_e32 v131, 1.0, v131
	v_rcp_f32_e32 v130, v130
	v_rcp_f32_e32 v131, v131
	v_rcp_f32_e32 v180, v180
	v_rcp_f32_e32 v206, v206
	v_cvt_pk_bf16_f32 v130, v130, v131
	ds_bpermute_b32 v130, v226, v130
	v_cvt_pk_bf16_f32 v131, v180, v206
	ds_bpermute_b32 v131, v226, v131
	v_mul_f32_e32 v180, 0xbfb8aa3b, v2
	v_mul_f32_e32 v206, 0xbfb8aa3b, v3
	v_exp_f32_e32 v180, v180
	v_exp_f32_e32 v206, v206
	s_waitcnt lgkmcnt(0)
	global_store_dwordx2 v[208:209], v[130:131], off offset:256
	v_mul_f32_e32 v130, 0xbfb8aa3b, v0
	v_mul_f32_e32 v131, 0xbfb8aa3b, v1
	v_exp_f32_e32 v130, v130
	v_exp_f32_e32 v131, v131
	v_add_f32_e32 v180, 1.0, v180
	v_add_f32_e32 v206, 1.0, v206
	v_add_f32_e32 v130, 1.0, v130
	v_add_f32_e32 v131, 1.0, v131
	v_rcp_f32_e32 v130, v130
	v_rcp_f32_e32 v131, v131
	v_rcp_f32_e32 v180, v180
	v_rcp_f32_e32 v206, v206
	v_cvt_pk_bf16_f32 v130, v130, v131
	ds_bpermute_b32 v130, v226, v130
	v_cvt_pk_bf16_f32 v131, v180, v206
	ds_bpermute_b32 v131, v226, v131
	s_waitcnt lgkmcnt(0)
	global_store_dwordx2 v[208:209], v[130:131], off offset:288

.LBB0_1024:
	s_waitcnt lgkmcnt(0)
	ds_read_b128 v[128:131], v179
	ds_read_b128 v[132:135], v179 offset:1024
	ds_read_b128 v[136:139], v179 offset:2048
	ds_read_b128 v[140:143], v179 offset:3072
	s_add_i32 s62, s36, 2
	s_add_u32 s37, s4, 0xfff80080
	s_addc_u32 s38, s5, -1
	s_cmp_eq_u32 s59, s36
	s_cselect_b32 s36, s58, s60
	s_cselect_b32 s39, s21, s38
	s_cselect_b32 s38, s25, s37
	s_cselect_b32 s37, s23, s61
	v_lshl_add_u64 v[166:167], s[4:5], 0, v[162:163]
	s_add_i32 m0, s31, 0xc000
	ds_read_b128 v[144:147], v190
	ds_read_b128 v[148:151], v190 offset:1024
	ds_read_b128 v[152:155], v190 offset:2048
	ds_read_b128 v[156:159], v190 offset:3072
	ds_read_b128 v[180:183], v190 offset:4096
	ds_read_b128 v[184:187], v190 offset:5120
	ds_read_b128 v[194:197], v190 offset:6144
	ds_read_b128 v[198:201], v190 offset:7168
	global_load_lds_dwordx4 v[166:167], off
	s_add_i32 m0, s31, 0xe000
	v_lshl_add_u64 v[166:167], s[4:5], 0, v[164:165]

	global_load_lds_dwordx4 v[166:167], off
	s_waitcnt lgkmcnt(8)
	s_barrier
	s_waitcnt lgkmcnt(0)


	v_mfma_f32_16x16x32_bf16 v[124:127], v[128:131], v[144:147], v[124:127]
	v_mfma_f32_16x16x32_bf16 v[120:123], v[136:139], v[144:147], v[120:123]
	v_mfma_f32_16x16x32_bf16 v[116:119], v[128:131], v[152:155], v[116:119]
	v_mfma_f32_16x16x32_bf16 v[104:107], v[136:139], v[152:155], v[104:107]
	v_mfma_f32_16x16x32_bf16 v[96:99], v[128:131], v[180:183], v[96:99]
	v_mfma_f32_16x16x32_bf16 v[88:91], v[136:139], v[180:183], v[88:91]
	v_mfma_f32_16x16x32_bf16 v[80:83], v[128:131], v[194:197], v[80:83]
	v_mfma_f32_16x16x32_bf16 v[72:75], v[136:139], v[194:197], v[72:75]
	v_mfma_f32_16x16x32_bf16 v[124:127], v[132:135], v[148:151], v[124:127]
	v_mfma_f32_16x16x32_bf16 v[120:123], v[140:143], v[148:151], v[120:123]
	v_mfma_f32_16x16x32_bf16 v[116:119], v[132:135], v[156:159], v[116:119]
	v_mfma_f32_16x16x32_bf16 v[104:107], v[140:143], v[156:159], v[104:107]
	v_mfma_f32_16x16x32_bf16 v[96:99], v[132:135], v[184:187], v[96:99]
	v_mfma_f32_16x16x32_bf16 v[88:91], v[140:143], v[184:187], v[88:91]
	v_mfma_f32_16x16x32_bf16 v[80:83], v[132:135], v[198:201], v[80:83]
	v_mfma_f32_16x16x32_bf16 v[72:75], v[140:143], v[198:201], v[72:75]

	s_barrier
	s_add_i32 s63, s52, s42
	v_lshl_add_u64 v[166:167], s[36:37], 0, v[172:173]
	s_mov_b32 m0, s63
	ds_read_b128 v[202:205], v191
	ds_read_b128 v[206:209], v191 offset:1024
	ds_read_b128 v[222:225], v191 offset:2048
	ds_read_b128 v[226:229], v191 offset:3072
	global_load_lds_dwordx4 v[166:167], off
	s_add_i32 m0, s63, 0x2000
	v_lshl_add_u64 v[188:189], s[36:37], 0, v[174:175]

	global_load_lds_dwordx4 v[188:189], off
	s_barrier
	s_waitcnt lgkmcnt(0)


	v_mfma_f32_16x16x32_bf16 v[112:115], v[202:205], v[144:147], v[112:115]
	v_mfma_f32_16x16x32_bf16 v[108:111], v[222:225], v[144:147], v[108:111]
	v_mfma_f32_16x16x32_bf16 v[100:103], v[202:205], v[152:155], v[100:103]
	v_mfma_f32_16x16x32_bf16 v[92:95], v[222:225], v[152:155], v[92:95]
	v_mfma_f32_16x16x32_bf16 v[84:87], v[202:205], v[180:183], v[84:87]
	v_mfma_f32_16x16x32_bf16 v[76:79], v[222:225], v[180:183], v[76:79]
	v_mfma_f32_16x16x32_bf16 v[68:71], v[202:205], v[194:197], v[68:71]
	v_mfma_f32_16x16x32_bf16 v[64:67], v[222:225], v[194:197], v[64:67]
	v_mfma_f32_16x16x32_bf16 v[112:115], v[206:209], v[148:151], v[112:115]
	v_mfma_f32_16x16x32_bf16 v[108:111], v[226:229], v[148:151], v[108:111]
	v_mfma_f32_16x16x32_bf16 v[100:103], v[206:209], v[156:159], v[100:103]
	v_mfma_f32_16x16x32_bf16 v[92:95], v[226:229], v[156:159], v[92:95]
	v_mfma_f32_16x16x32_bf16 v[84:87], v[206:209], v[184:187], v[84:87]
	v_mfma_f32_16x16x32_bf16 v[76:79], v[226:229], v[184:187], v[76:79]
	v_mfma_f32_16x16x32_bf16 v[68:71], v[206:209], v[198:201], v[68:71]
	v_mfma_f32_16x16x32_bf16 v[64:67], v[226:229], v[198:201], v[64:67]

	s_mov_b32 m0, s31
	v_lshl_add_u64 v[230:231], s[38:39], 0, v[172:173]
	s_barrier
	ds_read_b128 v[144:147], v190 offset:16384
	ds_read_b128 v[148:151], v190 offset:17408
	ds_read_b128 v[152:155], v190 offset:18432
	ds_read_b128 v[156:159], v190 offset:19456
	ds_read_b128 v[180:183], v190 offset:20480
	ds_read_b128 v[184:187], v190 offset:21504
	ds_read_b128 v[194:197], v190 offset:22528
	ds_read_b128 v[198:201], v190 offset:23552
	global_load_lds_dwordx4 v[230:231], off
	s_mov_b32 m0, s35
	v_lshl_add_u64 v[232:233], s[38:39], 0, v[174:175]

	global_load_lds_dwordx4 v[232:233], off
	s_barrier
	s_waitcnt lgkmcnt(0)


	v_mfma_f32_16x16x32_bf16 v[60:63], v[128:131], v[144:147], v[60:63]
	v_mfma_f32_16x16x32_bf16 v[56:59], v[136:139], v[144:147], v[56:59]
	v_mfma_f32_16x16x32_bf16 v[52:55], v[128:131], v[152:155], v[52:55]
	v_mfma_f32_16x16x32_bf16 v[40:43], v[136:139], v[152:155], v[40:43]
	v_mfma_f32_16x16x32_bf16 v[36:39], v[128:131], v[180:183], v[36:39]
	v_mfma_f32_16x16x32_bf16 v[24:27], v[136:139], v[180:183], v[24:27]
	v_mfma_f32_16x16x32_bf16 v[20:23], v[128:131], v[194:197], v[20:23]
	v_mfma_f32_16x16x32_bf16 v[8:11], v[136:139], v[194:197], v[8:11]
	v_mfma_f32_16x16x32_bf16 v[60:63], v[132:135], v[148:151], v[60:63]
	v_mfma_f32_16x16x32_bf16 v[56:59], v[140:143], v[148:151], v[56:59]
	v_mfma_f32_16x16x32_bf16 v[52:55], v[132:135], v[156:159], v[52:55]
	v_mfma_f32_16x16x32_bf16 v[40:43], v[140:143], v[156:159], v[40:43]
	v_mfma_f32_16x16x32_bf16 v[36:39], v[132:135], v[184:187], v[36:39]
	v_mfma_f32_16x16x32_bf16 v[24:27], v[140:143], v[184:187], v[24:27]
	v_mfma_f32_16x16x32_bf16 v[20:23], v[132:135], v[198:201], v[20:23]
	v_mfma_f32_16x16x32_bf16 v[8:11], v[140:143], v[198:201], v[8:11]

	s_barrier
	s_add_u32 s64, s36, 0x80000
	s_addc_u32 s65, s37, 0
	s_add_i32 s63, s53, s42
	s_mov_b32 m0, s63
	v_lshl_add_u64 v[128:129], s[64:65], 0, v[172:173]

	global_load_lds_dwordx4 v[128:129], off
	s_add_i32 m0, s63, 0x2000
	v_lshl_add_u64 v[128:129], s[64:65], 0, v[174:175]

	global_load_lds_dwordx4 v[128:129], off
	s_waitcnt vmcnt(6)
	s_barrier

	v_mfma_f32_16x16x32_bf16 v[48:51], v[202:205], v[144:147], v[48:51]
	v_mfma_f32_16x16x32_bf16 v[44:47], v[222:225], v[144:147], v[44:47]
	v_mfma_f32_16x16x32_bf16 v[32:35], v[202:205], v[152:155], v[32:35]
	v_mfma_f32_16x16x32_bf16 v[28:31], v[222:225], v[152:155], v[28:31]
	v_mfma_f32_16x16x32_bf16 v[16:19], v[202:205], v[180:183], v[16:19]
	v_mfma_f32_16x16x32_bf16 v[12:15], v[222:225], v[180:183], v[12:15]
	v_mfma_f32_16x16x32_bf16 v[4:7], v[202:205], v[194:197], v[4:7]
	v_mfma_f32_16x16x32_bf16 v[0:3], v[222:225], v[194:197], v[0:3]
	v_mfma_f32_16x16x32_bf16 v[48:51], v[206:209], v[148:151], v[48:51]
	v_mfma_f32_16x16x32_bf16 v[44:47], v[226:229], v[148:151], v[44:47]
	v_mfma_f32_16x16x32_bf16 v[32:35], v[206:209], v[156:159], v[32:35]
	v_mfma_f32_16x16x32_bf16 v[28:31], v[226:229], v[156:159], v[28:31]
	v_mfma_f32_16x16x32_bf16 v[16:19], v[206:209], v[184:187], v[16:19]
	v_mfma_f32_16x16x32_bf16 v[12:15], v[226:229], v[184:187], v[12:15]
	v_mfma_f32_16x16x32_bf16 v[4:7], v[206:209], v[198:201], v[4:7]
	v_mfma_f32_16x16x32_bf16 v[0:3], v[226:229], v[198:201], v[0:3]

	s_add_i32 s63, 0, 0x18000
	v_add_u32_e32 v140, s63, v177
	s_barrier
	ds_read_b128 v[128:131], v140
	ds_read_b128 v[132:135], v140 offset:1024
	ds_read_b128 v[136:139], v140 offset:2048
	ds_read_b128 v[140:143], v140 offset:3072
	s_add_u32 s38, s38, 0x80000
	s_addc_u32 s39, s39, 0
	s_mov_b32 m0, s43
	v_lshl_add_u64 v[202:203], s[38:39], 0, v[172:173]
	ds_read_b128 v[144:147], v190 offset:32768
	ds_read_b128 v[148:151], v190 offset:33792
	ds_read_b128 v[152:155], v190 offset:34816
	ds_read_b128 v[156:159], v190 offset:35840
	ds_read_b128 v[180:183], v190 offset:36864
	ds_read_b128 v[184:187], v190 offset:37888
	ds_read_b128 v[194:197], v190 offset:38912
	ds_read_b128 v[198:201], v190 offset:39936
	global_load_lds_dwordx4 v[202:203], off
	s_mov_b32 m0, s44
	v_lshl_add_u64 v[202:203], s[38:39], 0, v[174:175]

	global_load_lds_dwordx4 v[202:203], off
	s_waitcnt lgkmcnt(8)
	s_barrier
	s_waitcnt lgkmcnt(0)


	v_mfma_f32_16x16x32_bf16 v[124:127], v[128:131], v[144:147], v[124:127]
	v_mfma_f32_16x16x32_bf16 v[120:123], v[136:139], v[144:147], v[120:123]
	v_mfma_f32_16x16x32_bf16 v[116:119], v[128:131], v[152:155], v[116:119]
	v_mfma_f32_16x16x32_bf16 v[104:107], v[136:139], v[152:155], v[104:107]
	v_mfma_f32_16x16x32_bf16 v[96:99], v[128:131], v[180:183], v[96:99]
	v_mfma_f32_16x16x32_bf16 v[88:91], v[136:139], v[180:183], v[88:91]
	v_mfma_f32_16x16x32_bf16 v[80:83], v[128:131], v[194:197], v[80:83]
	v_mfma_f32_16x16x32_bf16 v[72:75], v[136:139], v[194:197], v[72:75]
	v_mfma_f32_16x16x32_bf16 v[124:127], v[132:135], v[148:151], v[124:127]
	v_mfma_f32_16x16x32_bf16 v[120:123], v[140:143], v[148:151], v[120:123]
	v_mfma_f32_16x16x32_bf16 v[116:119], v[132:135], v[156:159], v[116:119]
	v_mfma_f32_16x16x32_bf16 v[104:107], v[140:143], v[156:159], v[104:107]
	v_mfma_f32_16x16x32_bf16 v[96:99], v[132:135], v[184:187], v[96:99]
	v_mfma_f32_16x16x32_bf16 v[88:91], v[140:143], v[184:187], v[88:91]
	v_mfma_f32_16x16x32_bf16 v[80:83], v[132:135], v[198:201], v[80:83]
	v_mfma_f32_16x16x32_bf16 v[72:75], v[140:143], v[198:201], v[72:75]

	s_barrier
	s_add_i32 s38, 0, 0x1c000
	s_add_i32 s39, s63, s42
	v_add_u32_e32 v160, s38, v177
	v_lshl_add_u64 v[166:167], v[166:167], 0, s[14:15]
	s_mov_b32 m0, s39
	ds_read_b128 v[202:205], v160
	ds_read_b128 v[206:209], v160 offset:1024
	ds_read_b128 v[222:225], v160 offset:2048
	ds_read_b128 v[226:229], v160 offset:3072
	global_load_lds_dwordx4 v[166:167], off
	s_add_i32 m0, s39, 0x2000
	v_lshl_add_u64 v[166:167], v[188:189], 0, s[14:15]

	global_load_lds_dwordx4 v[166:167], off
	s_barrier
	s_waitcnt lgkmcnt(0)


	v_mfma_f32_16x16x32_bf16 v[112:115], v[202:205], v[144:147], v[112:115]
	v_mfma_f32_16x16x32_bf16 v[108:111], v[222:225], v[144:147], v[108:111]
	v_mfma_f32_16x16x32_bf16 v[100:103], v[202:205], v[152:155], v[100:103]
	v_mfma_f32_16x16x32_bf16 v[92:95], v[222:225], v[152:155], v[92:95]
	v_mfma_f32_16x16x32_bf16 v[84:87], v[202:205], v[180:183], v[84:87]
	v_mfma_f32_16x16x32_bf16 v[76:79], v[222:225], v[180:183], v[76:79]
	v_mfma_f32_16x16x32_bf16 v[68:71], v[202:205], v[194:197], v[68:71]
	v_mfma_f32_16x16x32_bf16 v[64:67], v[222:225], v[194:197], v[64:67]
	v_mfma_f32_16x16x32_bf16 v[112:115], v[206:209], v[148:151], v[112:115]
	v_mfma_f32_16x16x32_bf16 v[108:111], v[226:229], v[148:151], v[108:111]
	v_mfma_f32_16x16x32_bf16 v[100:103], v[206:209], v[156:159], v[100:103]
	v_mfma_f32_16x16x32_bf16 v[92:95], v[226:229], v[156:159], v[92:95]
	v_mfma_f32_16x16x32_bf16 v[84:87], v[206:209], v[184:187], v[84:87]
	v_mfma_f32_16x16x32_bf16 v[76:79], v[226:229], v[184:187], v[76:79]
	v_mfma_f32_16x16x32_bf16 v[68:71], v[206:209], v[198:201], v[68:71]
	v_mfma_f32_16x16x32_bf16 v[64:67], v[226:229], v[198:201], v[64:67]

	s_mov_b32 m0, s48
	v_lshl_add_u64 v[166:167], v[230:231], 0, s[14:15]
	s_barrier
	ds_read_b128 v[144:147], v190 offset:49152
	ds_read_b128 v[148:151], v190 offset:50176
	ds_read_b128 v[152:155], v190 offset:51200
	ds_read_b128 v[156:159], v190 offset:52224
	ds_read_b128 v[180:183], v190 offset:53248
	ds_read_b128 v[184:187], v190 offset:54272
	ds_read_b128 v[194:197], v190 offset:55296
	ds_read_b128 v[198:201], v190 offset:56320
	global_load_lds_dwordx4 v[166:167], off
	s_mov_b32 m0, s49
	v_lshl_add_u64 v[166:167], v[232:233], 0, s[14:15]

	global_load_lds_dwordx4 v[166:167], off
	s_barrier
	s_waitcnt lgkmcnt(0)


	v_mfma_f32_16x16x32_bf16 v[60:63], v[128:131], v[144:147], v[60:63]
	v_mfma_f32_16x16x32_bf16 v[56:59], v[136:139], v[144:147], v[56:59]
	v_mfma_f32_16x16x32_bf16 v[52:55], v[128:131], v[152:155], v[52:55]
	v_mfma_f32_16x16x32_bf16 v[40:43], v[136:139], v[152:155], v[40:43]
	v_mfma_f32_16x16x32_bf16 v[36:39], v[128:131], v[180:183], v[36:39]
	v_mfma_f32_16x16x32_bf16 v[24:27], v[136:139], v[180:183], v[24:27]
	v_mfma_f32_16x16x32_bf16 v[20:23], v[128:131], v[194:197], v[20:23]
	v_mfma_f32_16x16x32_bf16 v[8:11], v[136:139], v[194:197], v[8:11]
	v_mfma_f32_16x16x32_bf16 v[60:63], v[132:135], v[148:151], v[60:63]
	v_mfma_f32_16x16x32_bf16 v[56:59], v[140:143], v[148:151], v[56:59]
	v_mfma_f32_16x16x32_bf16 v[52:55], v[132:135], v[156:159], v[52:55]
	v_mfma_f32_16x16x32_bf16 v[40:43], v[140:143], v[156:159], v[40:43]
	v_mfma_f32_16x16x32_bf16 v[36:39], v[132:135], v[184:187], v[36:39]
	v_mfma_f32_16x16x32_bf16 v[24:27], v[140:143], v[184:187], v[24:27]
	v_mfma_f32_16x16x32_bf16 v[20:23], v[132:135], v[198:201], v[20:23]
	v_mfma_f32_16x16x32_bf16 v[8:11], v[140:143], v[198:201], v[8:11]

	s_barrier
	s_add_u32 s36, s36, 0x80080
	s_addc_u32 s37, s37, 0
	s_add_i32 s38, s38, s42
	s_mov_b32 m0, s38
	v_lshl_add_u64 v[128:129], s[36:37], 0, v[172:173]

	global_load_lds_dwordx4 v[128:129], off
	s_add_i32 m0, s38, 0x2000
	v_lshl_add_u64 v[128:129], s[36:37], 0, v[174:175]

	global_load_lds_dwordx4 v[128:129], off
	s_waitcnt vmcnt(6)
	s_barrier

	v_mfma_f32_16x16x32_bf16 v[48:51], v[202:205], v[144:147], v[48:51]
	v_mfma_f32_16x16x32_bf16 v[44:47], v[222:225], v[144:147], v[44:47]
	v_mfma_f32_16x16x32_bf16 v[32:35], v[202:205], v[152:155], v[32:35]
	v_mfma_f32_16x16x32_bf16 v[28:31], v[222:225], v[152:155], v[28:31]
	v_mfma_f32_16x16x32_bf16 v[16:19], v[202:205], v[180:183], v[16:19]
	v_mfma_f32_16x16x32_bf16 v[12:15], v[222:225], v[180:183], v[12:15]
	v_mfma_f32_16x16x32_bf16 v[4:7], v[202:205], v[194:197], v[4:7]
	v_mfma_f32_16x16x32_bf16 v[0:3], v[222:225], v[194:197], v[0:3]
	v_mfma_f32_16x16x32_bf16 v[48:51], v[206:209], v[148:151], v[48:51]
	v_mfma_f32_16x16x32_bf16 v[44:47], v[226:229], v[148:151], v[44:47]
	v_mfma_f32_16x16x32_bf16 v[32:35], v[206:209], v[156:159], v[32:35]
	v_mfma_f32_16x16x32_bf16 v[28:31], v[226:229], v[156:159], v[28:31]
	v_mfma_f32_16x16x32_bf16 v[16:19], v[206:209], v[184:187], v[16:19]
	v_mfma_f32_16x16x32_bf16 v[12:15], v[226:229], v[184:187], v[12:15]
	v_mfma_f32_16x16x32_bf16 v[4:7], v[206:209], v[198:201], v[4:7]
	v_mfma_f32_16x16x32_bf16 v[0:3], v[226:229], v[198:201], v[0:3]

	s_add_u32 s4, s4, 0x100
	s_addc_u32 s5, s5, 0
	s_add_u32 s60, s60, 0x100
	s_addc_u32 s61, s61, 0
	s_cmp_ge_i32 s62, s17
	s_mov_b32 s36, s62
	s_barrier
	s_cbranch_scc0 .LBB0_1024
	v_mov_b32_e32 v128, v210
	v_mov_b32_e32 v129, v169
	s_cmp_lt_i32 s12, 0
	v_lshl_add_u32 v128, v128, 4, v129
	v_ashrrev_i32_e32 v166, 2, v128
	v_and_b32_e32 v160, 3, v129
	v_and_b32_e32 v128, -4, v128
	v_lshl_add_u32 v193, v160, 6, v128
	s_mov_b64 s[4:5], -1
	s_cbranch_scc0 .LBB0_1043
	s_lshl_b32 s4, s30, 8
	v_lshl_or_b32 v128, v160, 2, s4
	s_lshl_b32 s4, s34, 8
	v_or_b32_e32 v180, s47, v128
	s_add_i32 s4, s4, s46
	v_readlane_b32 s60, v254, 6
	v_ashrrev_i32_e32 v181, 31, v180
	v_add_u32_e32 v184, s4, v166
	s_cmp_lt_i32 s34, 32
	v_readlane_b32 s61, v254, 7
	v_lshlrev_b64 v[128:129], 2, v[180:181]
	v_readlane_b32 s62, v254, 8
	v_readlane_b32 s63, v254, 9
	v_readlane_b32 s64, v254, 10
	v_readlane_b32 s65, v254, 11
	v_readlane_b32 s66, v254, 12
	v_readlane_b32 s67, v254, 13
	v_readlane_b32 s68, v254, 14
	v_readlane_b32 s69, v254, 15
	v_readlane_b32 s70, v254, 16
	v_readlane_b32 s71, v254, 17
	v_readlane_b32 s72, v254, 18
	v_readlane_b32 s73, v254, 19
	v_readlane_b32 s74, v254, 20
	v_readlane_b32 s75, v254, 21
	s_cselect_b32 s5, s61, s51
	s_cselect_b32 s4, s60, s50
	v_ashrrev_i32_e32 v185, 31, v184
	v_lshl_add_u64 v[182:183], s[4:5], 0, v[128:129]
	v_lshlrev_b64 v[130:131], 13, v[184:185]
	v_readlane_b32 s60, v254, 22
	v_lshl_add_u64 v[136:137], v[182:183], 0, v[130:131]
	v_readlane_b32 s61, v254, 23
	v_readlane_b32 s68, v254, 30
	v_readlane_b32 s69, v254, 31
	global_load_dwordx4 v[196:199], v[136:137], off nt
	global_load_dwordx4 v[200:203], v[136:137], off offset:64 nt
	global_load_dwordx4 v[204:207], v[136:137], off offset:512 nt
	s_mov_b64 s[60:61], s[68:69]
	v_lshl_add_u64 v[138:139], s[60:61], 0, v[128:129]
	global_load_dwordx4 v[140:143], v[138:139], off
	global_load_dwordx4 v[132:135], v[138:139], off offset:64
	global_load_dwordx4 v[128:131], v[138:139], off offset:512
	global_load_dwordx4 v[222:225], v[136:137], off offset:576 nt
	v_and_b32_e32 v145, 64, v192
	global_load_dwordx4 v[136:139], v[138:139], off offset:576
	v_xor_b32_e32 v144, 1, v192
	v_add_u32_e32 v194, 64, v145
	v_add_u32_e32 v186, 16, v184
	v_cmp_lt_i32_e64 s[4:5], v144, v194
	v_ashrrev_i32_e32 v187, 31, v186
	ds_bpermute_b32 v188, v193, v124
	v_cndmask_b32_e64 v195, v192, v144, s[4:5]
	v_lshlrev_b64 v[144:145], 13, v[186:187]
	v_lshl_add_u64 v[144:145], v[182:183], 0, v[144:145]
	global_load_dwordx4 v[156:159], v[144:145], off nt
	global_load_dwordx4 v[152:155], v[144:145], off offset:64 nt
	global_load_dwordx4 v[148:151], v[144:145], off offset:512 nt
	s_nop 0
	global_load_dwordx4 v[144:147], v[144:145], off offset:576 nt
	ds_bpermute_b32 v189, v193, v125
	ds_bpermute_b32 v208, v193, v126
	ds_bpermute_b32 v209, v193, v127
	ds_bpermute_b32 v226, v193, v120
	ds_bpermute_b32 v227, v193, v121
	ds_bpermute_b32 v228, v193, v122
	ds_bpermute_b32 v229, v193, v123
	ds_bpermute_b32 v230, v193, v112
	ds_bpermute_b32 v231, v193, v113
	v_readlane_b32 s64, v254, 26
	v_readlane_b32 s65, v254, 27
	v_readlane_b32 s66, v254, 28
	v_readlane_b32 s67, v254, 29
	v_readlane_b32 s72, v254, 34
	v_readlane_b32 s73, v254, 35
	v_readlane_b32 s74, v254, 36
	v_readlane_b32 s75, v254, 37
	s_mov_b64 s[64:65], s[72:73]
	ds_bpermute_b32 v232, v193, v114
	ds_bpermute_b32 v233, v193, v115
	v_lshlrev_b64 v[234:235], 11, v[184:185]
	s_mov_b64 s[66:67], s[74:75]
	v_lshl_add_u64 v[234:235], v[234:235], 0, v[180:181]
	v_xor_b32_e32 v167, 2, v192
	v_lshl_add_u64 v[236:237], v[234:235], 2, s[66:67]
	v_readlane_b32 s2, v254, 54
	v_cmp_lt_i32_e64 s[4:5], v167, v194
	v_lshlrev_b32_e32 v194, 2, v195
	v_lshlrev_b64 v[234:235], 1, v[234:235]
	v_readlane_b32 s3, v254, 55
	v_or_b32_e32 v240, 32, v234
	v_mov_b32_e32 v241, v235
	v_lshl_add_u64 v[238:239], s[2:3], 0, v[234:235]
	v_lshl_add_u64 v[240:241], s[2:3], 0, v[240:241]
	v_cndmask_b32_e64 v167, v192, v167, s[4:5]
	v_lshlrev_b32_e32 v167, 2, v167
	v_cmp_eq_u32_e32 vcc, 0, v160
	v_readlane_b32 s62, v254, 24
	v_readlane_b32 s63, v254, 25
	v_readlane_b32 s70, v254, 32
	v_readlane_b32 s71, v254, 33
	s_waitcnt vmcnt(0) lgkmcnt(0)
	v_pk_add_f32 v[198:199], v[198:199], v[208:209]
	v_pk_add_f32 v[196:197], v[196:197], v[188:189]
	v_pk_add_f32 v[202:203], v[202:203], v[228:229]
	v_pk_add_f32 v[200:201], v[200:201], v[226:227]
	v_pk_add_f32 v[204:205], v[204:205], v[230:231]
	v_mul_f32_e32 v195, v197, v197
	v_mul_f32_e32 v221, v199, v199
	global_store_dwordx4 v[236:237], v[196:199], off
	v_pk_mul_f32 v[188:189], v[142:143], v[198:199]
	v_pk_mul_f32 v[208:209], v[140:141], v[196:197]
	v_mul_f32_e32 v199, v201, v201
	v_mul_f32_e32 v230, v203, v203
	v_pk_mul_f32 v[226:227], v[134:135], v[202:203]
	v_pk_mul_f32 v[228:229], v[132:133], v[200:201]
	v_fmac_f32_e32 v195, v196, v196
	v_fmac_f32_e32 v221, v198, v198
	v_cvt_pk_bf16_f32 v196, v208, v209
	v_cvt_pk_bf16_f32 v197, v188, v189
	v_fmac_f32_e32 v199, v200, v200
	v_fmac_f32_e32 v230, v202, v202
	v_pk_add_f32 v[206:207], v[206:207], v[232:233]
	v_cvt_pk_bf16_f32 v188, v228, v229
	v_cvt_pk_bf16_f32 v189, v226, v227
	v_add_f32_e32 v195, v195, v221
	global_store_dwordx2 v[238:239], v[196:197], off
	v_add_f32_e32 v196, v199, v230
	global_store_dwordx4 v[236:237], v[200:203], off offset:64
	global_store_dwordx2 v[240:241], v[188:189], off
	v_add_f32_e32 v188, v195, v196
	v_mul_f32_e32 v189, v205, v205
	v_mul_f32_e32 v195, v207, v207
	v_fmac_f32_e32 v189, v204, v204
	v_fmac_f32_e32 v195, v206, v206
	ds_bpermute_b32 v200, v193, v108
	ds_bpermute_b32 v198, v193, v110
	ds_bpermute_b32 v199, v193, v111
	ds_bpermute_b32 v201, v193, v109
	v_add_f32_e32 v189, v189, v195
	v_add_f32_e32 v195, v188, v189
	v_pk_mul_f32 v[188:189], v[130:131], v[206:207]
	v_pk_mul_f32 v[196:197], v[128:129], v[204:205]
	global_store_dwordx4 v[236:237], v[204:207], off offset:512
	v_cvt_pk_bf16_f32 v196, v196, v197
	v_cvt_pk_bf16_f32 v197, v188, v189
	v_or_b32_e32 v188, 0x100, v234
	v_mov_b32_e32 v189, v235
	v_lshl_add_u64 v[188:189], s[2:3], 0, v[188:189]
	global_store_dwordx2 v[188:189], v[196:197], off
	s_waitcnt lgkmcnt(1)
	v_pk_add_f32 v[198:199], v[224:225], v[198:199]
	s_waitcnt lgkmcnt(0)
	v_pk_add_f32 v[196:197], v[222:223], v[200:201]
	v_mul_f32_e32 v189, v199, v199
	v_mul_f32_e32 v188, v197, v197
	v_fmac_f32_e32 v188, v196, v196
	v_fmac_f32_e32 v189, v198, v198
	v_add_f32_e32 v188, v188, v189
	v_add_f32_e32 v195, v195, v188
	ds_bpermute_b32 v200, v194, v195
	v_pk_mul_f32 v[188:189], v[136:137], v[196:197]
	global_store_dwordx4 v[236:237], v[196:199], off offset:576
	v_or_b32_e32 v234, 0x120, v234
	s_nop 0
	v_cvt_pk_bf16_f32 v196, v188, v189
	s_waitcnt lgkmcnt(0)
	v_add_f32_e32 v188, v195, v200
	ds_bpermute_b32 v189, v167, v188
	v_pk_mul_f32 v[198:199], v[138:139], v[198:199]
	s_nop 0
	v_cvt_pk_bf16_f32 v197, v198, v199
	v_lshl_add_u64 v[198:199], s[2:3], 0, v[234:235]
	global_store_dwordx2 v[198:199], v[196:197], off
	s_and_saveexec_b64 s[4:5], vcc
	s_cbranch_execz .LBB0_1028
	s_waitcnt lgkmcnt(0)
	v_add_f32_e32 v195, v188, v189
	s_lshl_b32 s36, s30, 2
	v_lshlrev_b64 v[188:189], 7, v[184:185]
	s_ashr_i32 s37, s36, 31
	v_lshl_add_u64 v[188:189], s[10:11], 0, v[188:189]
	v_lshl_add_u64 v[188:189], s[36:37], 2, v[188:189]
	s_lshl_b32 s36, s45, 2
	s_mov_b32 s37, s13
	v_lshl_add_u64 v[188:189], v[188:189], 0, s[36:37]
	global_store_dword v[188:189], v195, off

.LBB0_1167:
	ds_read_b128 v[148:151], v143
	ds_read_b128 v[152:155], v143 offset:1024
	ds_read_b128 v[156:159], v143 offset:2048
	ds_read_b128 v[160:163], v143 offset:3072
	s_add_u32 s24, s22, 0xfff80080
	s_addc_u32 s25, s23, -1
	s_cmp_eq_u32 s53, 28
	s_cselect_b32 s27, s15, s25
	s_cselect_b32 s26, s49, s24
	s_cselect_b32 s25, s13, s52
	s_cselect_b32 s24, s50, s51
	v_lshl_add_u64 v[136:137], s[22:23], 0, v[128:129]
	s_add_i32 m0, s21, 0xc000
	ds_read_b128 v[164:167], v145
	ds_read_b128 v[176:179], v145 offset:1024
	ds_read_b128 v[180:183], v145 offset:2048
	ds_read_b128 v[184:187], v145 offset:3072
	ds_read_b128 v[188:191], v145 offset:4096
	ds_read_b128 v[192:195], v145 offset:5120
	ds_read_b128 v[196:199], v145 offset:6144
	ds_read_b128 v[200:203], v145 offset:7168
	global_load_lds_dwordx4 v[136:137], off
	s_add_i32 m0, s21, 0xe000
	v_lshl_add_u64 v[136:137], s[22:23], 0, v[130:131]

	global_load_lds_dwordx4 v[136:137], off
	s_waitcnt lgkmcnt(8)
	s_barrier
	s_waitcnt lgkmcnt(0)


	v_mfma_f32_16x16x32_bf16 v[124:127], v[148:151], v[164:167], v[124:127]
	v_mfma_f32_16x16x32_bf16 v[120:123], v[156:159], v[164:167], v[120:123]
	v_mfma_f32_16x16x32_bf16 v[116:119], v[148:151], v[180:183], v[116:119]
	v_mfma_f32_16x16x32_bf16 v[104:107], v[156:159], v[180:183], v[104:107]
	v_mfma_f32_16x16x32_bf16 v[96:99], v[148:151], v[188:191], v[96:99]
	v_mfma_f32_16x16x32_bf16 v[88:91], v[156:159], v[188:191], v[88:91]
	v_mfma_f32_16x16x32_bf16 v[80:83], v[148:151], v[196:199], v[80:83]
	v_mfma_f32_16x16x32_bf16 v[72:75], v[156:159], v[196:199], v[72:75]
	v_mfma_f32_16x16x32_bf16 v[124:127], v[152:155], v[176:179], v[124:127]
	v_mfma_f32_16x16x32_bf16 v[120:123], v[160:163], v[176:179], v[120:123]
	v_mfma_f32_16x16x32_bf16 v[116:119], v[152:155], v[184:187], v[116:119]
	v_mfma_f32_16x16x32_bf16 v[104:107], v[160:163], v[184:187], v[104:107]
	v_mfma_f32_16x16x32_bf16 v[96:99], v[152:155], v[192:195], v[96:99]
	v_mfma_f32_16x16x32_bf16 v[88:91], v[160:163], v[192:195], v[88:91]
	v_mfma_f32_16x16x32_bf16 v[80:83], v[152:155], v[200:203], v[80:83]
	v_mfma_f32_16x16x32_bf16 v[72:75], v[160:163], v[200:203], v[72:75]

	s_barrier
	s_add_i32 s54, s45, s31
	v_lshl_add_u64 v[136:137], s[24:25], 0, v[172:173]
	s_mov_b32 m0, s54
	ds_read_b128 v[204:207], v147
	ds_read_b128 v[218:221], v147 offset:1024
	ds_read_b128 v[222:225], v147 offset:2048
	ds_read_b128 v[226:229], v147 offset:3072
	global_load_lds_dwordx4 v[136:137], off
	s_add_i32 m0, s54, 0x2000
	v_lshl_add_u64 v[140:141], s[24:25], 0, v[174:175]

	global_load_lds_dwordx4 v[140:141], off
	s_barrier
	s_waitcnt lgkmcnt(0)


	v_mfma_f32_16x16x32_bf16 v[112:115], v[204:207], v[164:167], v[112:115]
	v_mfma_f32_16x16x32_bf16 v[108:111], v[222:225], v[164:167], v[108:111]
	v_mfma_f32_16x16x32_bf16 v[100:103], v[204:207], v[180:183], v[100:103]
	v_mfma_f32_16x16x32_bf16 v[92:95], v[222:225], v[180:183], v[92:95]
	v_mfma_f32_16x16x32_bf16 v[84:87], v[204:207], v[188:191], v[84:87]
	v_mfma_f32_16x16x32_bf16 v[76:79], v[222:225], v[188:191], v[76:79]
	v_mfma_f32_16x16x32_bf16 v[68:71], v[204:207], v[196:199], v[68:71]
	v_mfma_f32_16x16x32_bf16 v[64:67], v[222:225], v[196:199], v[64:67]
	v_mfma_f32_16x16x32_bf16 v[112:115], v[218:221], v[176:179], v[112:115]
	v_mfma_f32_16x16x32_bf16 v[108:111], v[226:229], v[176:179], v[108:111]
	v_mfma_f32_16x16x32_bf16 v[100:103], v[218:221], v[184:187], v[100:103]
	v_mfma_f32_16x16x32_bf16 v[92:95], v[226:229], v[184:187], v[92:95]
	v_mfma_f32_16x16x32_bf16 v[84:87], v[218:221], v[192:195], v[84:87]
	v_mfma_f32_16x16x32_bf16 v[76:79], v[226:229], v[192:195], v[76:79]
	v_mfma_f32_16x16x32_bf16 v[68:71], v[218:221], v[200:203], v[68:71]
	v_mfma_f32_16x16x32_bf16 v[64:67], v[226:229], v[200:203], v[64:67]

	s_mov_b32 m0, s21
	v_lshl_add_u64 v[208:209], s[26:27], 0, v[172:173]
	s_barrier
	ds_read_b128 v[164:167], v145 offset:16384
	ds_read_b128 v[176:179], v145 offset:17408
	ds_read_b128 v[180:183], v145 offset:18432
	ds_read_b128 v[184:187], v145 offset:19456
	ds_read_b128 v[188:191], v145 offset:20480
	ds_read_b128 v[192:195], v145 offset:21504
	ds_read_b128 v[196:199], v145 offset:22528
	ds_read_b128 v[200:203], v145 offset:23552
	global_load_lds_dwordx4 v[208:209], off
	s_mov_b32 m0, s35
	v_lshl_add_u64 v[230:231], s[26:27], 0, v[174:175]

	global_load_lds_dwordx4 v[230:231], off
	s_barrier
	s_waitcnt lgkmcnt(0)


	v_mfma_f32_16x16x32_bf16 v[60:63], v[148:151], v[164:167], v[60:63]
	v_mfma_f32_16x16x32_bf16 v[56:59], v[156:159], v[164:167], v[56:59]
	v_mfma_f32_16x16x32_bf16 v[48:51], v[148:151], v[180:183], v[48:51]
	v_mfma_f32_16x16x32_bf16 v[40:43], v[156:159], v[180:183], v[40:43]
	v_mfma_f32_16x16x32_bf16 v[32:35], v[148:151], v[188:191], v[32:35]
	v_mfma_f32_16x16x32_bf16 v[24:27], v[156:159], v[188:191], v[24:27]
	v_mfma_f32_16x16x32_bf16 v[16:19], v[148:151], v[196:199], v[16:19]
	v_mfma_f32_16x16x32_bf16 v[8:11], v[156:159], v[196:199], v[8:11]
	v_mfma_f32_16x16x32_bf16 v[60:63], v[152:155], v[176:179], v[60:63]
	v_mfma_f32_16x16x32_bf16 v[56:59], v[160:163], v[176:179], v[56:59]
	v_mfma_f32_16x16x32_bf16 v[48:51], v[152:155], v[184:187], v[48:51]
	v_mfma_f32_16x16x32_bf16 v[40:43], v[160:163], v[184:187], v[40:43]
	v_mfma_f32_16x16x32_bf16 v[32:35], v[152:155], v[192:195], v[32:35]
	v_mfma_f32_16x16x32_bf16 v[24:27], v[160:163], v[192:195], v[24:27]
	v_mfma_f32_16x16x32_bf16 v[16:19], v[152:155], v[200:203], v[16:19]
	v_mfma_f32_16x16x32_bf16 v[8:11], v[160:163], v[200:203], v[8:11]

	s_barrier
	s_add_u32 s54, s24, 0x80000
	s_addc_u32 s55, s25, 0
	s_add_i32 s56, s46, s31
	s_mov_b32 m0, s56
	v_lshl_add_u64 v[148:149], s[54:55], 0, v[172:173]

	global_load_lds_dwordx4 v[148:149], off
	s_add_i32 m0, s56, 0x2000
	v_lshl_add_u64 v[148:149], s[54:55], 0, v[174:175]

	global_load_lds_dwordx4 v[148:149], off
	s_waitcnt vmcnt(6)
	s_barrier

	v_mfma_f32_16x16x32_bf16 v[52:55], v[204:207], v[164:167], v[52:55]
	v_mfma_f32_16x16x32_bf16 v[44:47], v[222:225], v[164:167], v[44:47]
	v_mfma_f32_16x16x32_bf16 v[36:39], v[204:207], v[180:183], v[36:39]
	v_mfma_f32_16x16x32_bf16 v[28:31], v[222:225], v[180:183], v[28:31]
	v_mfma_f32_16x16x32_bf16 v[20:23], v[204:207], v[188:191], v[20:23]
	v_mfma_f32_16x16x32_bf16 v[12:15], v[222:225], v[188:191], v[12:15]
	v_mfma_f32_16x16x32_bf16 v[4:7], v[204:207], v[196:199], v[4:7]
	v_mfma_f32_16x16x32_bf16 v[0:3], v[222:225], v[196:199], v[0:3]
	v_mfma_f32_16x16x32_bf16 v[52:55], v[218:221], v[176:179], v[52:55]
	v_mfma_f32_16x16x32_bf16 v[44:47], v[226:229], v[176:179], v[44:47]
	v_mfma_f32_16x16x32_bf16 v[36:39], v[218:221], v[184:187], v[36:39]
	v_mfma_f32_16x16x32_bf16 v[28:31], v[226:229], v[184:187], v[28:31]
	v_mfma_f32_16x16x32_bf16 v[20:23], v[218:221], v[192:195], v[20:23]
	v_mfma_f32_16x16x32_bf16 v[12:15], v[226:229], v[192:195], v[12:15]
	v_mfma_f32_16x16x32_bf16 v[4:7], v[218:221], v[200:203], v[4:7]
	v_mfma_f32_16x16x32_bf16 v[0:3], v[226:229], v[200:203], v[0:3]

	s_add_i32 s54, 0, 0x18000
	v_add_u32_e32 v138, s54, v139
	s_barrier
	ds_read_b128 v[148:151], v138
	ds_read_b128 v[152:155], v138 offset:1024
	ds_read_b128 v[156:159], v138 offset:2048
	ds_read_b128 v[160:163], v138 offset:3072
	s_add_u32 s26, s26, 0x80000
	s_addc_u32 s27, s27, 0
	s_mov_b32 m0, s36
	v_lshl_add_u64 v[204:205], s[26:27], 0, v[172:173]
	ds_read_b128 v[164:167], v145 offset:32768
	ds_read_b128 v[176:179], v145 offset:33792
	ds_read_b128 v[180:183], v145 offset:34816
	ds_read_b128 v[184:187], v145 offset:35840
	ds_read_b128 v[188:191], v145 offset:36864
	ds_read_b128 v[192:195], v145 offset:37888
	ds_read_b128 v[196:199], v145 offset:38912
	ds_read_b128 v[200:203], v145 offset:39936
	global_load_lds_dwordx4 v[204:205], off
	s_mov_b32 m0, s37
	v_lshl_add_u64 v[204:205], s[26:27], 0, v[174:175]

	global_load_lds_dwordx4 v[204:205], off
	s_waitcnt lgkmcnt(8)
	s_barrier
	s_waitcnt lgkmcnt(0)


	v_mfma_f32_16x16x32_bf16 v[124:127], v[148:151], v[164:167], v[124:127]
	v_mfma_f32_16x16x32_bf16 v[120:123], v[156:159], v[164:167], v[120:123]
	v_mfma_f32_16x16x32_bf16 v[116:119], v[148:151], v[180:183], v[116:119]
	v_mfma_f32_16x16x32_bf16 v[104:107], v[156:159], v[180:183], v[104:107]
	v_mfma_f32_16x16x32_bf16 v[96:99], v[148:151], v[188:191], v[96:99]
	v_mfma_f32_16x16x32_bf16 v[88:91], v[156:159], v[188:191], v[88:91]
	v_mfma_f32_16x16x32_bf16 v[80:83], v[148:151], v[196:199], v[80:83]
	v_mfma_f32_16x16x32_bf16 v[72:75], v[156:159], v[196:199], v[72:75]
	v_mfma_f32_16x16x32_bf16 v[124:127], v[152:155], v[176:179], v[124:127]
	v_mfma_f32_16x16x32_bf16 v[120:123], v[160:163], v[176:179], v[120:123]
	v_mfma_f32_16x16x32_bf16 v[116:119], v[152:155], v[184:187], v[116:119]
	v_mfma_f32_16x16x32_bf16 v[104:107], v[160:163], v[184:187], v[104:107]
	v_mfma_f32_16x16x32_bf16 v[96:99], v[152:155], v[192:195], v[96:99]
	v_mfma_f32_16x16x32_bf16 v[88:91], v[160:163], v[192:195], v[88:91]
	v_mfma_f32_16x16x32_bf16 v[80:83], v[152:155], v[200:203], v[80:83]
	v_mfma_f32_16x16x32_bf16 v[72:75], v[160:163], v[200:203], v[72:75]

	s_barrier
	s_add_i32 s26, 0, 0x1c000
	s_add_i32 s27, s54, s31
	v_add_u32_e32 v138, s26, v139
	v_lshl_add_u64 v[136:137], v[136:137], 0, s[10:11]
	s_mov_b32 m0, s27
	ds_read_b128 v[204:207], v138
	ds_read_b128 v[218:221], v138 offset:1024
	ds_read_b128 v[222:225], v138 offset:2048
	ds_read_b128 v[226:229], v138 offset:3072
	global_load_lds_dwordx4 v[136:137], off
	s_add_i32 m0, s27, 0x2000
	v_lshl_add_u64 v[136:137], v[140:141], 0, s[10:11]

	global_load_lds_dwordx4 v[136:137], off
	s_barrier
	s_waitcnt lgkmcnt(0)


	v_mfma_f32_16x16x32_bf16 v[112:115], v[204:207], v[164:167], v[112:115]
	v_mfma_f32_16x16x32_bf16 v[108:111], v[222:225], v[164:167], v[108:111]
	v_mfma_f32_16x16x32_bf16 v[100:103], v[204:207], v[180:183], v[100:103]
	v_mfma_f32_16x16x32_bf16 v[92:95], v[222:225], v[180:183], v[92:95]
	v_mfma_f32_16x16x32_bf16 v[84:87], v[204:207], v[188:191], v[84:87]
	v_mfma_f32_16x16x32_bf16 v[76:79], v[222:225], v[188:191], v[76:79]
	v_mfma_f32_16x16x32_bf16 v[68:71], v[204:207], v[196:199], v[68:71]
	v_mfma_f32_16x16x32_bf16 v[64:67], v[222:225], v[196:199], v[64:67]
	v_mfma_f32_16x16x32_bf16 v[112:115], v[218:221], v[176:179], v[112:115]
	v_mfma_f32_16x16x32_bf16 v[108:111], v[226:229], v[176:179], v[108:111]
	v_mfma_f32_16x16x32_bf16 v[100:103], v[218:221], v[184:187], v[100:103]
	v_mfma_f32_16x16x32_bf16 v[92:95], v[226:229], v[184:187], v[92:95]
	v_mfma_f32_16x16x32_bf16 v[84:87], v[218:221], v[192:195], v[84:87]
	v_mfma_f32_16x16x32_bf16 v[76:79], v[226:229], v[192:195], v[76:79]
	v_mfma_f32_16x16x32_bf16 v[68:71], v[218:221], v[200:203], v[68:71]
	v_mfma_f32_16x16x32_bf16 v[64:67], v[226:229], v[200:203], v[64:67]

	s_mov_b32 m0, s41
	v_lshl_add_u64 v[136:137], v[208:209], 0, s[10:11]
	s_barrier
	ds_read_b128 v[164:167], v145 offset:49152
	ds_read_b128 v[176:179], v145 offset:50176
	ds_read_b128 v[180:183], v145 offset:51200
	ds_read_b128 v[184:187], v145 offset:52224
	ds_read_b128 v[188:191], v145 offset:53248
	ds_read_b128 v[192:195], v145 offset:54272
	ds_read_b128 v[196:199], v145 offset:55296
	ds_read_b128 v[200:203], v145 offset:56320
	global_load_lds_dwordx4 v[136:137], off
	s_mov_b32 m0, s42
	v_lshl_add_u64 v[136:137], v[230:231], 0, s[10:11]

	global_load_lds_dwordx4 v[136:137], off
	s_barrier
	s_waitcnt lgkmcnt(0)


	v_mfma_f32_16x16x32_bf16 v[60:63], v[148:151], v[164:167], v[60:63]
	v_mfma_f32_16x16x32_bf16 v[56:59], v[156:159], v[164:167], v[56:59]
	v_mfma_f32_16x16x32_bf16 v[48:51], v[148:151], v[180:183], v[48:51]
	v_mfma_f32_16x16x32_bf16 v[40:43], v[156:159], v[180:183], v[40:43]
	v_mfma_f32_16x16x32_bf16 v[32:35], v[148:151], v[188:191], v[32:35]
	v_mfma_f32_16x16x32_bf16 v[24:27], v[156:159], v[188:191], v[24:27]
	v_mfma_f32_16x16x32_bf16 v[16:19], v[148:151], v[196:199], v[16:19]
	v_mfma_f32_16x16x32_bf16 v[8:11], v[156:159], v[196:199], v[8:11]
	v_mfma_f32_16x16x32_bf16 v[60:63], v[152:155], v[176:179], v[60:63]
	v_mfma_f32_16x16x32_bf16 v[56:59], v[160:163], v[176:179], v[56:59]
	v_mfma_f32_16x16x32_bf16 v[48:51], v[152:155], v[184:187], v[48:51]
	v_mfma_f32_16x16x32_bf16 v[40:43], v[160:163], v[184:187], v[40:43]
	v_mfma_f32_16x16x32_bf16 v[32:35], v[152:155], v[192:195], v[32:35]
	v_mfma_f32_16x16x32_bf16 v[24:27], v[160:163], v[192:195], v[24:27]
	v_mfma_f32_16x16x32_bf16 v[16:19], v[152:155], v[200:203], v[16:19]
	v_mfma_f32_16x16x32_bf16 v[8:11], v[160:163], v[200:203], v[8:11]

	s_barrier
	s_add_u32 s24, s24, 0x80080
	s_addc_u32 s25, s25, 0
	s_add_i32 s26, s26, s31
	s_mov_b32 m0, s26
	v_lshl_add_u64 v[136:137], s[24:25], 0, v[172:173]

	global_load_lds_dwordx4 v[136:137], off
	s_add_i32 m0, s26, 0x2000
	v_lshl_add_u64 v[136:137], s[24:25], 0, v[174:175]

	global_load_lds_dwordx4 v[136:137], off
	s_waitcnt vmcnt(6)
	s_barrier

	v_mfma_f32_16x16x32_bf16 v[52:55], v[204:207], v[164:167], v[52:55]
	v_mfma_f32_16x16x32_bf16 v[44:47], v[222:225], v[164:167], v[44:47]
	v_mfma_f32_16x16x32_bf16 v[36:39], v[204:207], v[180:183], v[36:39]
	v_mfma_f32_16x16x32_bf16 v[28:31], v[222:225], v[180:183], v[28:31]
	v_mfma_f32_16x16x32_bf16 v[20:23], v[204:207], v[188:191], v[20:23]
	v_mfma_f32_16x16x32_bf16 v[12:15], v[222:225], v[188:191], v[12:15]
	v_mfma_f32_16x16x32_bf16 v[4:7], v[204:207], v[196:199], v[4:7]
	v_mfma_f32_16x16x32_bf16 v[0:3], v[222:225], v[196:199], v[0:3]
	v_mfma_f32_16x16x32_bf16 v[52:55], v[218:221], v[176:179], v[52:55]
	v_mfma_f32_16x16x32_bf16 v[44:47], v[226:229], v[176:179], v[44:47]
	v_mfma_f32_16x16x32_bf16 v[36:39], v[218:221], v[184:187], v[36:39]
	v_mfma_f32_16x16x32_bf16 v[28:31], v[226:229], v[184:187], v[28:31]
	v_mfma_f32_16x16x32_bf16 v[20:23], v[218:221], v[192:195], v[20:23]
	v_mfma_f32_16x16x32_bf16 v[12:15], v[226:229], v[192:195], v[12:15]
	v_mfma_f32_16x16x32_bf16 v[4:7], v[218:221], v[200:203], v[4:7]
	v_mfma_f32_16x16x32_bf16 v[0:3], v[226:229], v[200:203], v[0:3]

	s_add_i32 s53, s53, 2
	s_add_u32 s22, s22, 0x100
	s_addc_u32 s23, s23, 0
	s_add_u32 s51, s51, 0x100
	s_addc_u32 s52, s52, 0
	s_cmp_gt_u32 s53, 29
	s_barrier
	s_cbranch_scc0 .LBB0_1167
	s_lshl_b32 s13, s20, 8
	v_mov_b32_e32 v138, v210
	v_mov_b32_e32 v142, v169
	s_add_i32 s13, s13, s39
	s_lshl_b32 s15, s48, 7
	v_add_u32_e32 v136, s13, v142
	v_ashrrev_i32_e32 v137, 31, v136
	v_lshl_add_u64 v[140:141], v[136:137], 2, s[2:3]
	global_load_dword v154, v[140:141], off
	global_load_dword v152, v[140:141], off offset:64
	v_lshl_add_u32 v138, v138, 4, v142
	v_and_b32_e32 v142, 3, v142
	v_ashrrev_i32_e32 v144, 2, v138
	v_and_b32_e32 v138, -4, v138
	v_lshl_or_b32 v146, v142, 2, s15
	v_add_u32_e32 v151, s13, v144
	v_lshl_add_u32 v149, v142, 6, v138
	v_or_b32_e32 v156, s40, v146
	global_load_dword v150, v[140:141], off offset:128
	global_load_dword v148, v[140:141], off offset:192
	global_load_dword v146, v[140:141], off offset:512
	global_load_dword v144, v[140:141], off offset:576
	global_load_dword v142, v[140:141], off offset:640
	global_load_dword v138, v[140:141], off offset:704
	v_mov_b64_e32 v[136:137], s[0:1]
	v_ashrrev_i32_e32 v157, 31, v156
	v_mad_i64_i32 v[158:159], s[22:23], v151, s47, v[136:137]
	v_lshlrev_b64 v[140:141], 1, v[156:157]
	v_lshl_add_u64 v[156:157], v[158:159], 0, v[140:141]
	v_add_u32_e32 v153, 16, v151
	s_and_b64 vcc, exec, s[4:5]
	s_mov_b32 s48, s12
	s_mov_b32 s20, s14
	s_mov_b64 s[24:25], s[18:19]
	s_waitcnt vmcnt(0)
	v_pk_mul_f32 v[126:127], v[126:127], v[154:155] op_sel_hi:[1,0]
	v_pk_mul_f32 v[124:125], v[124:125], v[154:155] op_sel_hi:[1,0]
	v_pk_mul_f32 v[114:115], v[114:115], v[154:155] op_sel_hi:[1,0]
	v_pk_mul_f32 v[112:113], v[112:113], v[154:155] op_sel_hi:[1,0]
	v_pk_mul_f32 v[122:123], v[122:123], v[154:155] op_sel_hi:[1,0]
	v_pk_mul_f32 v[120:121], v[120:121], v[154:155] op_sel_hi:[1,0]
	v_pk_mul_f32 v[110:111], v[110:111], v[154:155] op_sel_hi:[1,0]
	v_pk_mul_f32 v[108:109], v[108:109], v[154:155] op_sel_hi:[1,0]
	v_mul_f32_e32 v154, 0xbfb8aa3b, v124
	v_mul_f32_e32 v155, 0xbfb8aa3b, v125
	v_mul_f32_e32 v158, 0xbfb8aa3b, v126
	v_mul_f32_e32 v159, 0xbfb8aa3b, v127
	v_mul_f32_e32 v160, 0xbfb8aa3b, v120
	v_mul_f32_e32 v161, 0xbfb8aa3b, v121
	v_mul_f32_e32 v162, 0xbfb8aa3b, v122
	v_mul_f32_e32 v163, 0xbfb8aa3b, v123
	v_exp_f32_e32 v154, v154
	v_exp_f32_e32 v155, v155
	v_exp_f32_e32 v158, v158
	v_exp_f32_e32 v159, v159
	v_exp_f32_e32 v160, v160
	v_exp_f32_e32 v161, v161
	v_exp_f32_e32 v162, v162
	v_exp_f32_e32 v163, v163
	v_add_f32_e32 v154, 1.0, v154
	v_add_f32_e32 v155, 1.0, v155
	v_add_f32_e32 v158, 1.0, v158
	v_add_f32_e32 v159, 1.0, v159
	v_add_f32_e32 v160, 1.0, v160
	v_add_f32_e32 v161, 1.0, v161
	v_add_f32_e32 v162, 1.0, v162
	v_add_f32_e32 v163, 1.0, v163
	v_rcp_f32_e32 v154, v154
	v_rcp_f32_e32 v155, v155
	v_rcp_f32_e32 v158, v158
	v_rcp_f32_e32 v159, v159
	v_rcp_f32_e32 v160, v160
	v_rcp_f32_e32 v161, v161
	v_rcp_f32_e32 v162, v162
	v_rcp_f32_e32 v163, v163
	v_pk_mul_f32 v[124:125], v[124:125], v[154:155]
	v_pk_mul_f32 v[126:127], v[126:127], v[158:159]
	v_pk_mul_f32 v[120:121], v[120:121], v[160:161]
	v_pk_mul_f32 v[122:123], v[122:123], v[162:163]
	v_pk_mul_f32 v[112:113], v[112:113], v[124:125]
	v_pk_mul_f32 v[114:115], v[114:115], v[126:127]
	v_pk_mul_f32 v[118:119], v[118:119], v[152:153] op_sel_hi:[1,0]
	v_pk_mul_f32 v[116:117], v[116:117], v[152:153] op_sel_hi:[1,0]
	v_pk_mul_f32 v[108:109], v[108:109], v[120:121]
	v_pk_mul_f32 v[110:111], v[110:111], v[122:123]
	v_cvt_pk_bf16_f32 v112, v112, v113
	v_cvt_pk_bf16_f32 v113, v114, v115
	v_mul_f32_e32 v164, 0xbfb8aa3b, v116
	v_mul_f32_e32 v165, 0xbfb8aa3b, v117
	v_mul_f32_e32 v166, 0xbfb8aa3b, v118
	v_mul_f32_e32 v167, 0xbfb8aa3b, v119
	v_cvt_pk_bf16_f32 v114, v108, v109
	v_cvt_pk_bf16_f32 v111, v110, v111
	ds_bpermute_b32 v108, v149, v112
	ds_bpermute_b32 v109, v149, v113
	v_exp_f32_e32 v164, v164
	v_exp_f32_e32 v165, v165
	v_exp_f32_e32 v166, v166
	v_exp_f32_e32 v167, v167
	ds_bpermute_b32 v110, v149, v114
	ds_bpermute_b32 v111, v149, v111
	v_add_f32_e32 v164, 1.0, v164
	v_add_f32_e32 v113, 1.0, v165
	s_waitcnt lgkmcnt(0)
	global_store_dwordx2 v[156:157], v[108:109], off
	global_store_dwordx2 v[156:157], v[110:111], off offset:32
	v_add_f32_e32 v108, 1.0, v166
	v_add_f32_e32 v109, 1.0, v167
	v_rcp_f32_e32 v112, v164
	v_rcp_f32_e32 v113, v113
	v_rcp_f32_e32 v108, v108
	v_rcp_f32_e32 v109, v109
	v_pk_mul_f32 v[102:103], v[102:103], v[152:153] op_sel_hi:[1,0]
	v_pk_mul_f32 v[100:101], v[100:101], v[152:153] op_sel_hi:[1,0]
	v_pk_mul_f32 v[110:111], v[116:117], v[112:113]
	v_pk_mul_f32 v[108:109], v[118:119], v[108:109]
	v_pk_mul_f32 v[100:101], v[100:101], v[110:111]
	v_pk_mul_f32 v[102:103], v[102:103], v[108:109]
	v_cvt_pk_bf16_f32 v100, v100, v101
	v_cvt_pk_bf16_f32 v101, v102, v103
	v_pk_mul_f32 v[102:103], v[106:107], v[152:153] op_sel_hi:[1,0]
	v_pk_mul_f32 v[104:105], v[104:105], v[152:153] op_sel_hi:[1,0]
	v_mul_f32_e32 v108, 0xbfb8aa3b, v102
	v_mul_f32_e32 v106, 0xbfb8aa3b, v104
	v_mul_f32_e32 v107, 0xbfb8aa3b, v105
	v_mul_f32_e32 v109, 0xbfb8aa3b, v103
	v_exp_f32_e32 v106, v106
	v_exp_f32_e32 v107, v107
	v_exp_f32_e32 v108, v108
	v_exp_f32_e32 v109, v109
	v_add_f32_e32 v106, 1.0, v106
	v_add_f32_e32 v107, 1.0, v107
	v_add_f32_e32 v108, 1.0, v108
	v_add_f32_e32 v109, 1.0, v109
	v_rcp_f32_e32 v106, v106
	v_rcp_f32_e32 v107, v107
	v_rcp_f32_e32 v108, v108
	v_rcp_f32_e32 v109, v109
	v_pk_mul_f32 v[94:95], v[94:95], v[152:153] op_sel_hi:[1,0]
	v_pk_mul_f32 v[92:93], v[92:93], v[152:153] op_sel_hi:[1,0]
	v_pk_mul_f32 v[104:105], v[104:105], v[106:107]
	v_pk_mul_f32 v[102:103], v[102:103], v[108:109]
	v_pk_mul_f32 v[92:93], v[92:93], v[104:105]
	v_pk_mul_f32 v[94:95], v[94:95], v[102:103]
	ds_bpermute_b32 v100, v149, v100
	ds_bpermute_b32 v101, v149, v101
	v_cvt_pk_bf16_f32 v92, v92, v93
	v_cvt_pk_bf16_f32 v93, v94, v95
	ds_bpermute_b32 v92, v149, v92
	ds_bpermute_b32 v93, v149, v93
	v_mad_i64_i32 v[94:95], s[22:23], v153, s47, v[136:137]
	v_lshl_add_u64 v[94:95], v[94:95], 0, v[140:141]
	s_waitcnt lgkmcnt(2)
	global_store_dwordx2 v[94:95], v[100:101], off
	s_waitcnt lgkmcnt(0)
	global_store_dwordx2 v[94:95], v[92:93], off offset:32
	v_pk_mul_f32 v[92:93], v[98:99], v[150:151] op_sel_hi:[1,0]
	v_pk_mul_f32 v[94:95], v[96:97], v[150:151] op_sel_hi:[1,0]
	v_mul_f32_e32 v98, 0xbfb8aa3b, v92
	v_mul_f32_e32 v96, 0xbfb8aa3b, v94
	v_mul_f32_e32 v97, 0xbfb8aa3b, v95
	v_mul_f32_e32 v99, 0xbfb8aa3b, v93
	v_exp_f32_e32 v96, v96
	v_exp_f32_e32 v97, v97
	v_exp_f32_e32 v98, v98
	v_exp_f32_e32 v99, v99
	v_add_f32_e32 v96, 1.0, v96
	v_add_f32_e32 v97, 1.0, v97
	v_add_f32_e32 v98, 1.0, v98
	v_add_f32_e32 v99, 1.0, v99
	v_rcp_f32_e32 v96, v96
	v_rcp_f32_e32 v97, v97
	v_rcp_f32_e32 v98, v98
	v_rcp_f32_e32 v99, v99
	v_pk_mul_f32 v[86:87], v[86:87], v[150:151] op_sel_hi:[1,0]
	v_pk_mul_f32 v[84:85], v[84:85], v[150:151] op_sel_hi:[1,0]
	v_pk_mul_f32 v[94:95], v[94:95], v[96:97]
	v_pk_mul_f32 v[92:93], v[92:93], v[98:99]
	v_pk_mul_f32 v[84:85], v[84:85], v[94:95]
	v_pk_mul_f32 v[86:87], v[86:87], v[92:93]
	v_cvt_pk_bf16_f32 v84, v84, v85
	v_cvt_pk_bf16_f32 v85, v86, v87
	v_pk_mul_f32 v[86:87], v[90:91], v[150:151] op_sel_hi:[1,0]
	v_pk_mul_f32 v[88:89], v[88:89], v[150:151] op_sel_hi:[1,0]
	v_mul_f32_e32 v92, 0xbfb8aa3b, v86
	v_mul_f32_e32 v90, 0xbfb8aa3b, v88
	v_mul_f32_e32 v91, 0xbfb8aa3b, v89
	v_mul_f32_e32 v93, 0xbfb8aa3b, v87
	v_exp_f32_e32 v90, v90
	v_exp_f32_e32 v91, v91
	v_exp_f32_e32 v92, v92
	v_exp_f32_e32 v93, v93
	v_add_f32_e32 v90, 1.0, v90
	v_add_f32_e32 v91, 1.0, v91
	v_add_f32_e32 v92, 1.0, v92
	v_add_f32_e32 v93, 1.0, v93
	v_rcp_f32_e32 v90, v90
	v_rcp_f32_e32 v91, v91
	v_rcp_f32_e32 v92, v92
	v_rcp_f32_e32 v93, v93
	v_pk_mul_f32 v[78:79], v[78:79], v[150:151] op_sel_hi:[1,0]
	v_pk_mul_f32 v[76:77], v[76:77], v[150:151] op_sel_hi:[1,0]
	v_pk_mul_f32 v[88:89], v[88:89], v[90:91]
	v_pk_mul_f32 v[86:87], v[86:87], v[92:93]
	v_pk_mul_f32 v[76:77], v[76:77], v[88:89]
	v_pk_mul_f32 v[78:79], v[78:79], v[86:87]
	ds_bpermute_b32 v84, v149, v84
	ds_bpermute_b32 v85, v149, v85
	v_cvt_pk_bf16_f32 v76, v76, v77
	v_cvt_pk_bf16_f32 v77, v78, v79
	ds_bpermute_b32 v76, v149, v76
	ds_bpermute_b32 v77, v149, v77
	v_add_u32_e32 v100, 32, v151
	v_mad_i64_i32 v[78:79], s[22:23], v100, s47, v[136:137]
	v_lshl_add_u64 v[78:79], v[78:79], 0, v[140:141]
	s_waitcnt lgkmcnt(2)
	global_store_dwordx2 v[78:79], v[84:85], off
	s_waitcnt lgkmcnt(0)
	global_store_dwordx2 v[78:79], v[76:77], off offset:32
	v_pk_mul_f32 v[76:77], v[82:83], v[148:149] op_sel_hi:[1,0]
	v_pk_mul_f32 v[78:79], v[80:81], v[148:149] op_sel_hi:[1,0]
	v_mul_f32_e32 v82, 0xbfb8aa3b, v76
	v_mul_f32_e32 v80, 0xbfb8aa3b, v78
	v_mul_f32_e32 v81, 0xbfb8aa3b, v79
	v_mul_f32_e32 v83, 0xbfb8aa3b, v77
	v_exp_f32_e32 v80, v80
	v_exp_f32_e32 v81, v81
	v_exp_f32_e32 v82, v82
	v_exp_f32_e32 v83, v83
	v_add_f32_e32 v80, 1.0, v80
	v_add_f32_e32 v81, 1.0, v81
	v_add_f32_e32 v82, 1.0, v82
	v_add_f32_e32 v83, 1.0, v83
	v_rcp_f32_e32 v80, v80
	v_rcp_f32_e32 v81, v81
	v_rcp_f32_e32 v82, v82
	v_rcp_f32_e32 v83, v83
	v_pk_mul_f32 v[70:71], v[70:71], v[148:149] op_sel_hi:[1,0]
	v_pk_mul_f32 v[68:69], v[68:69], v[148:149] op_sel_hi:[1,0]
	v_pk_mul_f32 v[78:79], v[78:79], v[80:81]
	v_pk_mul_f32 v[76:77], v[76:77], v[82:83]
	v_pk_mul_f32 v[68:69], v[68:69], v[78:79]
	v_pk_mul_f32 v[70:71], v[70:71], v[76:77]
	v_cvt_pk_bf16_f32 v68, v68, v69
	v_cvt_pk_bf16_f32 v69, v70, v71
	v_pk_mul_f32 v[70:71], v[74:75], v[148:149] op_sel_hi:[1,0]
	v_pk_mul_f32 v[72:73], v[72:73], v[148:149] op_sel_hi:[1,0]
	v_mul_f32_e32 v76, 0xbfb8aa3b, v70
	v_mul_f32_e32 v74, 0xbfb8aa3b, v72
	v_mul_f32_e32 v75, 0xbfb8aa3b, v73
	v_mul_f32_e32 v77, 0xbfb8aa3b, v71
	v_exp_f32_e32 v74, v74
	v_exp_f32_e32 v75, v75
	v_exp_f32_e32 v76, v76
	v_exp_f32_e32 v77, v77
	v_add_f32_e32 v74, 1.0, v74
	v_add_f32_e32 v75, 1.0, v75
	v_add_f32_e32 v76, 1.0, v76
	v_add_f32_e32 v77, 1.0, v77
	v_rcp_f32_e32 v74, v74
	v_rcp_f32_e32 v75, v75
	v_rcp_f32_e32 v76, v76
	v_rcp_f32_e32 v77, v77
	v_pk_mul_f32 v[66:67], v[66:67], v[148:149] op_sel_hi:[1,0]
	v_pk_mul_f32 v[64:65], v[64:65], v[148:149] op_sel_hi:[1,0]
	v_pk_mul_f32 v[72:73], v[72:73], v[74:75]
	v_pk_mul_f32 v[70:71], v[70:71], v[76:77]
	v_pk_mul_f32 v[64:65], v[64:65], v[72:73]
	v_pk_mul_f32 v[66:67], v[66:67], v[70:71]
	ds_bpermute_b32 v68, v149, v68
	ds_bpermute_b32 v69, v149, v69
	v_cvt_pk_bf16_f32 v64, v64, v65
	v_cvt_pk_bf16_f32 v65, v66, v67
	ds_bpermute_b32 v64, v149, v64
	ds_bpermute_b32 v65, v149, v65
	v_add_u32_e32 v84, 48, v151
	v_mad_i64_i32 v[66:67], s[22:23], v84, s47, v[136:137]
	v_lshl_add_u64 v[66:67], v[66:67], 0, v[140:141]
	v_pk_mul_f32 v[60:61], v[60:61], v[146:147] op_sel_hi:[1,0]
	s_waitcnt lgkmcnt(2)
	global_store_dwordx2 v[66:67], v[68:69], off
	s_waitcnt lgkmcnt(0)
	global_store_dwordx2 v[66:67], v[64:65], off offset:32
	v_pk_mul_f32 v[62:63], v[62:63], v[146:147] op_sel_hi:[1,0]
	v_mul_f32_e32 v64, 0xbfb8aa3b, v60
	v_mul_f32_e32 v65, 0xbfb8aa3b, v61
	v_exp_f32_e32 v64, v64
	v_exp_f32_e32 v65, v65
	v_mul_f32_e32 v66, 0xbfb8aa3b, v62
	v_mul_f32_e32 v67, 0xbfb8aa3b, v63
	v_exp_f32_e32 v66, v66
	v_exp_f32_e32 v67, v67
	v_add_f32_e32 v64, 1.0, v64
	v_add_f32_e32 v65, 1.0, v65
	v_rcp_f32_e32 v64, v64
	v_rcp_f32_e32 v65, v65
	v_add_f32_e32 v66, 1.0, v66
	v_add_f32_e32 v67, 1.0, v67
	v_rcp_f32_e32 v66, v66
	v_rcp_f32_e32 v67, v67
	v_pk_mul_f32 v[52:53], v[52:53], v[146:147] op_sel_hi:[1,0]
	v_pk_mul_f32 v[60:61], v[60:61], v[64:65]
	v_pk_mul_f32 v[54:55], v[54:55], v[146:147] op_sel_hi:[1,0]
	v_pk_mul_f32 v[52:53], v[52:53], v[60:61]
	v_pk_mul_f32 v[60:61], v[62:63], v[66:67]
	v_cvt_pk_bf16_f32 v52, v52, v53
	v_pk_mul_f32 v[54:55], v[54:55], v[60:61]
	v_pk_mul_f32 v[56:57], v[56:57], v[146:147] op_sel_hi:[1,0]
	v_cvt_pk_bf16_f32 v53, v54, v55
	v_pk_mul_f32 v[54:55], v[58:59], v[146:147] op_sel_hi:[1,0]
	v_mul_f32_e32 v58, 0xbfb8aa3b, v56
	v_mul_f32_e32 v59, 0xbfb8aa3b, v57
	v_mul_f32_e32 v60, 0xbfb8aa3b, v54
	v_mul_f32_e32 v61, 0xbfb8aa3b, v55
	v_exp_f32_e32 v58, v58
	v_exp_f32_e32 v59, v59
	v_exp_f32_e32 v60, v60
	v_exp_f32_e32 v61, v61
	v_add_f32_e32 v58, 1.0, v58
	v_add_f32_e32 v59, 1.0, v59
	v_add_f32_e32 v60, 1.0, v60
	v_add_f32_e32 v61, 1.0, v61
	v_rcp_f32_e32 v58, v58
	v_rcp_f32_e32 v59, v59
	v_rcp_f32_e32 v60, v60
	v_rcp_f32_e32 v61, v61
	v_pk_mul_f32 v[46:47], v[46:47], v[146:147] op_sel_hi:[1,0]
	v_pk_mul_f32 v[44:45], v[44:45], v[146:147] op_sel_hi:[1,0]
	v_pk_mul_f32 v[56:57], v[56:57], v[58:59]
	v_pk_mul_f32 v[54:55], v[54:55], v[60:61]
	v_pk_mul_f32 v[44:45], v[44:45], v[56:57]
	v_pk_mul_f32 v[46:47], v[46:47], v[54:55]
	ds_bpermute_b32 v52, v149, v52
	ds_bpermute_b32 v53, v149, v53
	v_cvt_pk_bf16_f32 v44, v44, v45
	v_cvt_pk_bf16_f32 v45, v46, v47
	ds_bpermute_b32 v44, v149, v44
	ds_bpermute_b32 v45, v149, v45
	v_add_u32_e32 v68, 0x80, v151
	v_mad_i64_i32 v[46:47], s[22:23], v68, s47, v[136:137]
	v_lshl_add_u64 v[46:47], v[46:47], 0, v[140:141]
	s_waitcnt lgkmcnt(2)
	global_store_dwordx2 v[46:47], v[52:53], off
	s_waitcnt lgkmcnt(0)
	global_store_dwordx2 v[46:47], v[44:45], off offset:32
	v_pk_mul_f32 v[44:45], v[50:51], v[144:145] op_sel_hi:[1,0]
	v_pk_mul_f32 v[46:47], v[48:49], v[144:145] op_sel_hi:[1,0]
	v_mul_f32_e32 v50, 0xbfb8aa3b, v44
	v_mul_f32_e32 v48, 0xbfb8aa3b, v46
	v_mul_f32_e32 v49, 0xbfb8aa3b, v47
	v_mul_f32_e32 v51, 0xbfb8aa3b, v45
	v_exp_f32_e32 v48, v48
	v_exp_f32_e32 v49, v49
	v_exp_f32_e32 v50, v50
	v_exp_f32_e32 v51, v51
	v_add_f32_e32 v48, 1.0, v48
	v_add_f32_e32 v49, 1.0, v49
	v_add_f32_e32 v50, 1.0, v50
	v_add_f32_e32 v51, 1.0, v51
	v_rcp_f32_e32 v48, v48
	v_rcp_f32_e32 v49, v49
	v_rcp_f32_e32 v50, v50
	v_rcp_f32_e32 v51, v51
	v_pk_mul_f32 v[38:39], v[38:39], v[144:145] op_sel_hi:[1,0]
	v_pk_mul_f32 v[36:37], v[36:37], v[144:145] op_sel_hi:[1,0]
	v_pk_mul_f32 v[46:47], v[46:47], v[48:49]
	v_pk_mul_f32 v[44:45], v[44:45], v[50:51]
	v_pk_mul_f32 v[36:37], v[36:37], v[46:47]
	v_pk_mul_f32 v[38:39], v[38:39], v[44:45]
	v_cvt_pk_bf16_f32 v36, v36, v37
	v_cvt_pk_bf16_f32 v37, v38, v39
	v_pk_mul_f32 v[38:39], v[42:43], v[144:145] op_sel_hi:[1,0]
	v_pk_mul_f32 v[40:41], v[40:41], v[144:145] op_sel_hi:[1,0]
	v_mul_f32_e32 v44, 0xbfb8aa3b, v38
	v_mul_f32_e32 v42, 0xbfb8aa3b, v40
	v_mul_f32_e32 v43, 0xbfb8aa3b, v41
	v_mul_f32_e32 v45, 0xbfb8aa3b, v39
	v_exp_f32_e32 v42, v42
	v_exp_f32_e32 v43, v43
	v_exp_f32_e32 v44, v44
	v_exp_f32_e32 v45, v45
	v_add_f32_e32 v42, 1.0, v42
	v_add_f32_e32 v43, 1.0, v43
	v_add_f32_e32 v44, 1.0, v44
	v_add_f32_e32 v45, 1.0, v45
	v_rcp_f32_e32 v42, v42
	v_rcp_f32_e32 v43, v43
	v_rcp_f32_e32 v44, v44
	v_rcp_f32_e32 v45, v45
	v_pk_mul_f32 v[30:31], v[30:31], v[144:145] op_sel_hi:[1,0]
	v_pk_mul_f32 v[28:29], v[28:29], v[144:145] op_sel_hi:[1,0]
	v_pk_mul_f32 v[40:41], v[40:41], v[42:43]
	v_pk_mul_f32 v[38:39], v[38:39], v[44:45]
	v_pk_mul_f32 v[28:29], v[28:29], v[40:41]
	v_pk_mul_f32 v[30:31], v[30:31], v[38:39]
	ds_bpermute_b32 v36, v149, v36
	ds_bpermute_b32 v37, v149, v37
	v_cvt_pk_bf16_f32 v28, v28, v29
	v_cvt_pk_bf16_f32 v29, v30, v31
	ds_bpermute_b32 v28, v149, v28
	ds_bpermute_b32 v29, v149, v29
	v_add_u32_e32 v52, 0x90, v151
	v_mad_i64_i32 v[30:31], s[22:23], v52, s47, v[136:137]
	v_lshl_add_u64 v[30:31], v[30:31], 0, v[140:141]
	s_waitcnt lgkmcnt(2)
	global_store_dwordx2 v[30:31], v[36:37], off
	s_waitcnt lgkmcnt(0)
	global_store_dwordx2 v[30:31], v[28:29], off offset:32
	v_pk_mul_f32 v[28:29], v[34:35], v[142:143] op_sel_hi:[1,0]
	v_pk_mul_f32 v[30:31], v[32:33], v[142:143] op_sel_hi:[1,0]
	v_mul_f32_e32 v34, 0xbfb8aa3b, v28
	v_mul_f32_e32 v32, 0xbfb8aa3b, v30
	v_mul_f32_e32 v33, 0xbfb8aa3b, v31
	v_mul_f32_e32 v35, 0xbfb8aa3b, v29
	v_exp_f32_e32 v32, v32
	v_exp_f32_e32 v33, v33
	v_exp_f32_e32 v34, v34
	v_exp_f32_e32 v35, v35
	v_add_f32_e32 v32, 1.0, v32
	v_add_f32_e32 v33, 1.0, v33
	v_add_f32_e32 v34, 1.0, v34
	v_add_f32_e32 v35, 1.0, v35
	v_rcp_f32_e32 v32, v32
	v_rcp_f32_e32 v33, v33
	v_rcp_f32_e32 v34, v34
	v_rcp_f32_e32 v35, v35
	v_pk_mul_f32 v[22:23], v[22:23], v[142:143] op_sel_hi:[1,0]
	v_pk_mul_f32 v[20:21], v[20:21], v[142:143] op_sel_hi:[1,0]
	v_pk_mul_f32 v[30:31], v[30:31], v[32:33]
	v_pk_mul_f32 v[28:29], v[28:29], v[34:35]
	v_pk_mul_f32 v[20:21], v[20:21], v[30:31]
	v_pk_mul_f32 v[22:23], v[22:23], v[28:29]
	v_cvt_pk_bf16_f32 v20, v20, v21
	v_cvt_pk_bf16_f32 v21, v22, v23
	v_pk_mul_f32 v[22:23], v[26:27], v[142:143] op_sel_hi:[1,0]
	v_pk_mul_f32 v[24:25], v[24:25], v[142:143] op_sel_hi:[1,0]
	v_mul_f32_e32 v28, 0xbfb8aa3b, v22
	v_mul_f32_e32 v26, 0xbfb8aa3b, v24
	v_mul_f32_e32 v27, 0xbfb8aa3b, v25
	v_mul_f32_e32 v29, 0xbfb8aa3b, v23
	v_exp_f32_e32 v26, v26
	v_exp_f32_e32 v27, v27
	v_exp_f32_e32 v28, v28
	v_exp_f32_e32 v29, v29
	v_add_f32_e32 v26, 1.0, v26
	v_add_f32_e32 v27, 1.0, v27
	v_add_f32_e32 v28, 1.0, v28
	v_add_f32_e32 v29, 1.0, v29
	v_rcp_f32_e32 v26, v26
	v_rcp_f32_e32 v27, v27
	v_rcp_f32_e32 v28, v28
	v_rcp_f32_e32 v29, v29
	v_pk_mul_f32 v[14:15], v[14:15], v[142:143] op_sel_hi:[1,0]
	v_pk_mul_f32 v[12:13], v[12:13], v[142:143] op_sel_hi:[1,0]
	v_pk_mul_f32 v[24:25], v[24:25], v[26:27]
	v_pk_mul_f32 v[22:23], v[22:23], v[28:29]
	v_pk_mul_f32 v[12:13], v[12:13], v[24:25]
	v_pk_mul_f32 v[14:15], v[14:15], v[22:23]
	ds_bpermute_b32 v20, v149, v20
	ds_bpermute_b32 v21, v149, v21
	v_cvt_pk_bf16_f32 v12, v12, v13
	v_cvt_pk_bf16_f32 v13, v14, v15
	ds_bpermute_b32 v12, v149, v12
	ds_bpermute_b32 v13, v149, v13
	v_add_u32_e32 v36, 0xa0, v151
	v_mad_i64_i32 v[14:15], s[22:23], v36, s47, v[136:137]
	v_lshl_add_u64 v[14:15], v[14:15], 0, v[140:141]
	s_waitcnt lgkmcnt(2)
	global_store_dwordx2 v[14:15], v[20:21], off
	s_waitcnt lgkmcnt(0)
	global_store_dwordx2 v[14:15], v[12:13], off offset:32
	v_pk_mul_f32 v[12:13], v[18:19], v[138:139] op_sel_hi:[1,0]
	v_pk_mul_f32 v[14:15], v[16:17], v[138:139] op_sel_hi:[1,0]
	v_mul_f32_e32 v18, 0xbfb8aa3b, v12
	v_mul_f32_e32 v16, 0xbfb8aa3b, v14
	v_mul_f32_e32 v17, 0xbfb8aa3b, v15
	v_mul_f32_e32 v19, 0xbfb8aa3b, v13
	v_exp_f32_e32 v16, v16
	v_exp_f32_e32 v17, v17
	v_exp_f32_e32 v18, v18
	v_exp_f32_e32 v19, v19
	v_add_f32_e32 v16, 1.0, v16
	v_add_f32_e32 v17, 1.0, v17
	v_add_f32_e32 v18, 1.0, v18
	v_add_f32_e32 v19, 1.0, v19
	v_rcp_f32_e32 v16, v16
	v_rcp_f32_e32 v17, v17
	v_rcp_f32_e32 v18, v18
	v_rcp_f32_e32 v19, v19
	v_pk_mul_f32 v[6:7], v[6:7], v[138:139] op_sel_hi:[1,0]
	v_pk_mul_f32 v[4:5], v[4:5], v[138:139] op_sel_hi:[1,0]
	v_pk_mul_f32 v[14:15], v[14:15], v[16:17]
	v_pk_mul_f32 v[12:13], v[12:13], v[18:19]
	v_pk_mul_f32 v[4:5], v[4:5], v[14:15]
	v_pk_mul_f32 v[6:7], v[6:7], v[12:13]
	v_cvt_pk_bf16_f32 v4, v4, v5
	v_cvt_pk_bf16_f32 v5, v6, v7
	v_pk_mul_f32 v[6:7], v[10:11], v[138:139] op_sel_hi:[1,0]
	v_pk_mul_f32 v[8:9], v[8:9], v[138:139] op_sel_hi:[1,0]
	v_mul_f32_e32 v12, 0xbfb8aa3b, v6
	v_mul_f32_e32 v10, 0xbfb8aa3b, v8
	v_mul_f32_e32 v11, 0xbfb8aa3b, v9
	v_mul_f32_e32 v13, 0xbfb8aa3b, v7
	v_exp_f32_e32 v10, v10
	v_exp_f32_e32 v11, v11
	v_exp_f32_e32 v12, v12
	v_exp_f32_e32 v13, v13
	v_add_f32_e32 v10, 1.0, v10
	v_add_f32_e32 v11, 1.0, v11
	v_add_f32_e32 v12, 1.0, v12
	v_add_f32_e32 v13, 1.0, v13
	v_rcp_f32_e32 v10, v10
	v_rcp_f32_e32 v11, v11
	v_rcp_f32_e32 v12, v12
	v_rcp_f32_e32 v13, v13
	v_pk_mul_f32 v[2:3], v[2:3], v[138:139] op_sel_hi:[1,0]
	v_pk_mul_f32 v[0:1], v[0:1], v[138:139] op_sel_hi:[1,0]
	v_pk_mul_f32 v[8:9], v[8:9], v[10:11]
	v_pk_mul_f32 v[6:7], v[6:7], v[12:13]
	v_pk_mul_f32 v[0:1], v[0:1], v[8:9]
	v_pk_mul_f32 v[2:3], v[2:3], v[6:7]
	ds_bpermute_b32 v4, v149, v4
	ds_bpermute_b32 v5, v149, v5
	v_cvt_pk_bf16_f32 v0, v0, v1
	v_cvt_pk_bf16_f32 v1, v2, v3
	ds_bpermute_b32 v0, v149, v0
	ds_bpermute_b32 v1, v149, v1
	v_add_u32_e32 v20, 0xb0, v151
	v_mad_i64_i32 v[2:3], s[22:23], v20, s47, v[136:137]
	v_lshl_add_u64 v[2:3], v[2:3], 0, v[140:141]
	s_mov_b64 s[22:23], s[16:17]
	s_waitcnt lgkmcnt(2)
	global_store_dwordx2 v[2:3], v[4:5], off
	s_waitcnt lgkmcnt(0)
	global_store_dwordx2 v[2:3], v[0:1], off offset:32
	s_cbranch_vccz .LBB0_1164
	s_waitcnt vmcnt(0)
	s_cmpk_gt_u32 s28, 0xff
	s_cbranch_scc1 .LBB0_1171
	s_barrier

.LBB0_1258:
	ds_read_b128 v[128:131], v159
	ds_read_b128 v[132:135], v159 offset:1024
	ds_read_b128 v[136:139], v159 offset:2048
	ds_read_b128 v[150:153], v159 offset:3072
	s_add_i32 s54, s18, 2
	s_add_u32 s19, s16, 0xffea0080
	s_addc_u32 s20, s17, -1
	s_cmp_eq_u32 s13, s18
	s_cselect_b32 s18, s4, s52
	s_cselect_b32 s21, s15, s20
	s_cselect_b32 s20, s14, s19
	s_cselect_b32 s19, s5, s53
	v_lshl_add_u64 v[166:167], s[16:17], 0, v[146:147]
	s_add_i32 m0, s26, 0xc000
	ds_read_b128 v[154:157], v160
	ds_read_b128 v[162:165], v160 offset:1024
	ds_read_b128 v[172:175], v160 offset:2048
	ds_read_b128 v[176:179], v160 offset:3072
	ds_read_b128 v[180:183], v160 offset:4096
	ds_read_b128 v[184:187], v160 offset:5120
	ds_read_b128 v[188:191], v160 offset:6144
	ds_read_b128 v[192:195], v160 offset:7168
	global_load_lds_dwordx4 v[166:167], off
	s_add_i32 m0, s26, 0xe000
	v_lshl_add_u64 v[166:167], s[16:17], 0, v[148:149]

	global_load_lds_dwordx4 v[166:167], off
	s_waitcnt lgkmcnt(8)
	s_barrier
	s_waitcnt lgkmcnt(0)


	v_mfma_f32_16x16x32_bf16 v[124:127], v[128:131], v[154:157], v[124:127]
	v_mfma_f32_16x16x32_bf16 v[120:123], v[136:139], v[154:157], v[120:123]
	v_mfma_f32_16x16x32_bf16 v[116:119], v[128:131], v[172:175], v[116:119]
	v_mfma_f32_16x16x32_bf16 v[104:107], v[136:139], v[172:175], v[104:107]
	v_mfma_f32_16x16x32_bf16 v[96:99], v[128:131], v[180:183], v[96:99]
	v_mfma_f32_16x16x32_bf16 v[88:91], v[136:139], v[180:183], v[88:91]
	v_mfma_f32_16x16x32_bf16 v[80:83], v[128:131], v[188:191], v[80:83]
	v_mfma_f32_16x16x32_bf16 v[72:75], v[136:139], v[188:191], v[72:75]
	v_mfma_f32_16x16x32_bf16 v[124:127], v[132:135], v[162:165], v[124:127]
	v_mfma_f32_16x16x32_bf16 v[120:123], v[150:153], v[162:165], v[120:123]
	v_mfma_f32_16x16x32_bf16 v[116:119], v[132:135], v[176:179], v[116:119]
	v_mfma_f32_16x16x32_bf16 v[104:107], v[150:153], v[176:179], v[104:107]
	v_mfma_f32_16x16x32_bf16 v[96:99], v[132:135], v[184:187], v[96:99]
	v_mfma_f32_16x16x32_bf16 v[88:91], v[150:153], v[184:187], v[88:91]
	v_mfma_f32_16x16x32_bf16 v[80:83], v[132:135], v[192:195], v[80:83]
	v_mfma_f32_16x16x32_bf16 v[72:75], v[150:153], v[192:195], v[72:75]

	s_barrier
	s_add_i32 s55, s35, s25
	v_lshl_add_u64 v[166:167], s[18:19], 0, v[140:141]
	s_mov_b32 m0, s55
	ds_read_b128 v[196:199], v161
	ds_read_b128 v[200:203], v161 offset:1024
	ds_read_b128 v[204:207], v161 offset:2048
	ds_read_b128 v[212:215], v161 offset:3072
	global_load_lds_dwordx4 v[166:167], off
	s_add_i32 m0, s55, 0x2000
	v_lshl_add_u64 v[208:209], s[18:19], 0, v[142:143]

	global_load_lds_dwordx4 v[208:209], off
	s_barrier
	s_waitcnt lgkmcnt(0)


	v_mfma_f32_16x16x32_bf16 v[112:115], v[196:199], v[154:157], v[112:115]
	v_mfma_f32_16x16x32_bf16 v[108:111], v[204:207], v[154:157], v[108:111]
	v_mfma_f32_16x16x32_bf16 v[100:103], v[196:199], v[172:175], v[100:103]
	v_mfma_f32_16x16x32_bf16 v[92:95], v[204:207], v[172:175], v[92:95]
	v_mfma_f32_16x16x32_bf16 v[84:87], v[196:199], v[180:183], v[84:87]
	v_mfma_f32_16x16x32_bf16 v[76:79], v[204:207], v[180:183], v[76:79]
	v_mfma_f32_16x16x32_bf16 v[68:71], v[196:199], v[188:191], v[68:71]
	v_mfma_f32_16x16x32_bf16 v[64:67], v[204:207], v[188:191], v[64:67]
	v_mfma_f32_16x16x32_bf16 v[112:115], v[200:203], v[162:165], v[112:115]
	v_mfma_f32_16x16x32_bf16 v[108:111], v[212:215], v[162:165], v[108:111]
	v_mfma_f32_16x16x32_bf16 v[100:103], v[200:203], v[176:179], v[100:103]
	v_mfma_f32_16x16x32_bf16 v[92:95], v[212:215], v[176:179], v[92:95]
	v_mfma_f32_16x16x32_bf16 v[84:87], v[200:203], v[184:187], v[84:87]
	v_mfma_f32_16x16x32_bf16 v[76:79], v[212:215], v[184:187], v[76:79]
	v_mfma_f32_16x16x32_bf16 v[68:71], v[200:203], v[192:195], v[68:71]
	v_mfma_f32_16x16x32_bf16 v[64:67], v[212:215], v[192:195], v[64:67]

	s_mov_b32 m0, s26
	v_lshl_add_u64 v[216:217], s[20:21], 0, v[140:141]
	s_barrier
	ds_read_b128 v[154:157], v160 offset:16384
	ds_read_b128 v[162:165], v160 offset:17408
	ds_read_b128 v[172:175], v160 offset:18432
	ds_read_b128 v[176:179], v160 offset:19456
	ds_read_b128 v[180:183], v160 offset:20480
	ds_read_b128 v[184:187], v160 offset:21504
	ds_read_b128 v[188:191], v160 offset:22528
	ds_read_b128 v[192:195], v160 offset:23552
	global_load_lds_dwordx4 v[216:217], off
	s_mov_b32 m0, s27
	v_lshl_add_u64 v[218:219], s[20:21], 0, v[142:143]

	global_load_lds_dwordx4 v[218:219], off
	s_barrier
	s_waitcnt lgkmcnt(0)


	v_mfma_f32_16x16x32_bf16 v[60:63], v[128:131], v[154:157], v[60:63]
	v_mfma_f32_16x16x32_bf16 v[56:59], v[136:139], v[154:157], v[56:59]
	v_mfma_f32_16x16x32_bf16 v[52:55], v[128:131], v[172:175], v[52:55]
	v_mfma_f32_16x16x32_bf16 v[40:43], v[136:139], v[172:175], v[40:43]
	v_mfma_f32_16x16x32_bf16 v[36:39], v[128:131], v[180:183], v[36:39]
	v_mfma_f32_16x16x32_bf16 v[24:27], v[136:139], v[180:183], v[24:27]
	v_mfma_f32_16x16x32_bf16 v[20:23], v[128:131], v[188:191], v[20:23]
	v_mfma_f32_16x16x32_bf16 v[8:11], v[136:139], v[188:191], v[8:11]
	v_mfma_f32_16x16x32_bf16 v[60:63], v[132:135], v[162:165], v[60:63]
	v_mfma_f32_16x16x32_bf16 v[56:59], v[150:153], v[162:165], v[56:59]
	v_mfma_f32_16x16x32_bf16 v[52:55], v[132:135], v[176:179], v[52:55]
	v_mfma_f32_16x16x32_bf16 v[40:43], v[150:153], v[176:179], v[40:43]
	v_mfma_f32_16x16x32_bf16 v[36:39], v[132:135], v[184:187], v[36:39]
	v_mfma_f32_16x16x32_bf16 v[24:27], v[150:153], v[184:187], v[24:27]
	v_mfma_f32_16x16x32_bf16 v[20:23], v[132:135], v[192:195], v[20:23]
	v_mfma_f32_16x16x32_bf16 v[8:11], v[150:153], v[192:195], v[8:11]

	s_barrier
	s_add_u32 s56, s18, 0x160000
	s_addc_u32 s57, s19, 0
	s_add_i32 s55, s36, s25
	s_mov_b32 m0, s55
	v_lshl_add_u64 v[128:129], s[56:57], 0, v[140:141]

	global_load_lds_dwordx4 v[128:129], off
	s_add_i32 m0, s55, 0x2000
	v_lshl_add_u64 v[128:129], s[56:57], 0, v[142:143]

	global_load_lds_dwordx4 v[128:129], off
	s_waitcnt vmcnt(6)
	s_barrier

	v_mfma_f32_16x16x32_bf16 v[48:51], v[196:199], v[154:157], v[48:51]
	v_mfma_f32_16x16x32_bf16 v[44:47], v[204:207], v[154:157], v[44:47]
	v_mfma_f32_16x16x32_bf16 v[32:35], v[196:199], v[172:175], v[32:35]
	v_mfma_f32_16x16x32_bf16 v[28:31], v[204:207], v[172:175], v[28:31]
	v_mfma_f32_16x16x32_bf16 v[16:19], v[196:199], v[180:183], v[16:19]
	v_mfma_f32_16x16x32_bf16 v[12:15], v[204:207], v[180:183], v[12:15]
	v_mfma_f32_16x16x32_bf16 v[4:7], v[196:199], v[188:191], v[4:7]
	v_mfma_f32_16x16x32_bf16 v[0:3], v[204:207], v[188:191], v[0:3]
	v_mfma_f32_16x16x32_bf16 v[48:51], v[200:203], v[162:165], v[48:51]
	v_mfma_f32_16x16x32_bf16 v[44:47], v[212:215], v[162:165], v[44:47]
	v_mfma_f32_16x16x32_bf16 v[32:35], v[200:203], v[176:179], v[32:35]
	v_mfma_f32_16x16x32_bf16 v[28:31], v[212:215], v[176:179], v[28:31]
	v_mfma_f32_16x16x32_bf16 v[16:19], v[200:203], v[184:187], v[16:19]
	v_mfma_f32_16x16x32_bf16 v[12:15], v[212:215], v[184:187], v[12:15]
	v_mfma_f32_16x16x32_bf16 v[4:7], v[200:203], v[192:195], v[4:7]
	v_mfma_f32_16x16x32_bf16 v[0:3], v[212:215], v[192:195], v[0:3]

	s_add_i32 s55, 0, 0x18000
	v_add_u32_e32 v144, s55, v158
	s_barrier
	ds_read_b128 v[128:131], v144
	ds_read_b128 v[132:135], v144 offset:1024
	ds_read_b128 v[136:139], v144 offset:2048
	ds_read_b128 v[150:153], v144 offset:3072
	s_add_u32 s20, s20, 0x160000
	s_addc_u32 s21, s21, 0
	s_mov_b32 m0, s28
	v_lshl_add_u64 v[196:197], s[20:21], 0, v[140:141]
	ds_read_b128 v[154:157], v160 offset:32768
	ds_read_b128 v[162:165], v160 offset:33792
	ds_read_b128 v[172:175], v160 offset:34816
	ds_read_b128 v[176:179], v160 offset:35840
	ds_read_b128 v[180:183], v160 offset:36864
	ds_read_b128 v[184:187], v160 offset:37888
	ds_read_b128 v[188:191], v160 offset:38912
	ds_read_b128 v[192:195], v160 offset:39936
	global_load_lds_dwordx4 v[196:197], off
	s_mov_b32 m0, s29
	v_lshl_add_u64 v[196:197], s[20:21], 0, v[142:143]

	global_load_lds_dwordx4 v[196:197], off
	s_waitcnt lgkmcnt(8)
	s_barrier
	s_waitcnt lgkmcnt(0)


	v_mfma_f32_16x16x32_bf16 v[124:127], v[128:131], v[154:157], v[124:127]
	v_mfma_f32_16x16x32_bf16 v[120:123], v[136:139], v[154:157], v[120:123]
	v_mfma_f32_16x16x32_bf16 v[116:119], v[128:131], v[172:175], v[116:119]
	v_mfma_f32_16x16x32_bf16 v[104:107], v[136:139], v[172:175], v[104:107]
	v_mfma_f32_16x16x32_bf16 v[96:99], v[128:131], v[180:183], v[96:99]
	v_mfma_f32_16x16x32_bf16 v[88:91], v[136:139], v[180:183], v[88:91]
	v_mfma_f32_16x16x32_bf16 v[80:83], v[128:131], v[188:191], v[80:83]
	v_mfma_f32_16x16x32_bf16 v[72:75], v[136:139], v[188:191], v[72:75]
	v_mfma_f32_16x16x32_bf16 v[124:127], v[132:135], v[162:165], v[124:127]
	v_mfma_f32_16x16x32_bf16 v[120:123], v[150:153], v[162:165], v[120:123]
	v_mfma_f32_16x16x32_bf16 v[116:119], v[132:135], v[176:179], v[116:119]
	v_mfma_f32_16x16x32_bf16 v[104:107], v[150:153], v[176:179], v[104:107]
	v_mfma_f32_16x16x32_bf16 v[96:99], v[132:135], v[184:187], v[96:99]
	v_mfma_f32_16x16x32_bf16 v[88:91], v[150:153], v[184:187], v[88:91]
	v_mfma_f32_16x16x32_bf16 v[80:83], v[132:135], v[192:195], v[80:83]
	v_mfma_f32_16x16x32_bf16 v[72:75], v[150:153], v[192:195], v[72:75]

	s_barrier
	s_add_i32 s20, 0, 0x1c000
	s_add_i32 s21, s55, s25
	v_add_u32_e32 v144, s20, v158
	v_lshl_add_u64 v[166:167], v[166:167], 0, s[6:7]
	s_mov_b32 m0, s21
	ds_read_b128 v[196:199], v144
	ds_read_b128 v[200:203], v144 offset:1024
	ds_read_b128 v[204:207], v144 offset:2048
	ds_read_b128 v[212:215], v144 offset:3072
	global_load_lds_dwordx4 v[166:167], off
	s_add_i32 m0, s21, 0x2000
	v_lshl_add_u64 v[166:167], v[208:209], 0, s[6:7]

	global_load_lds_dwordx4 v[166:167], off
	s_barrier
	s_waitcnt lgkmcnt(0)


	v_mfma_f32_16x16x32_bf16 v[112:115], v[196:199], v[154:157], v[112:115]
	v_mfma_f32_16x16x32_bf16 v[108:111], v[204:207], v[154:157], v[108:111]
	v_mfma_f32_16x16x32_bf16 v[100:103], v[196:199], v[172:175], v[100:103]
	v_mfma_f32_16x16x32_bf16 v[92:95], v[204:207], v[172:175], v[92:95]
	v_mfma_f32_16x16x32_bf16 v[84:87], v[196:199], v[180:183], v[84:87]
	v_mfma_f32_16x16x32_bf16 v[76:79], v[204:207], v[180:183], v[76:79]
	v_mfma_f32_16x16x32_bf16 v[68:71], v[196:199], v[188:191], v[68:71]
	v_mfma_f32_16x16x32_bf16 v[64:67], v[204:207], v[188:191], v[64:67]
	v_mfma_f32_16x16x32_bf16 v[112:115], v[200:203], v[162:165], v[112:115]
	v_mfma_f32_16x16x32_bf16 v[108:111], v[212:215], v[162:165], v[108:111]
	v_mfma_f32_16x16x32_bf16 v[100:103], v[200:203], v[176:179], v[100:103]
	v_mfma_f32_16x16x32_bf16 v[92:95], v[212:215], v[176:179], v[92:95]
	v_mfma_f32_16x16x32_bf16 v[84:87], v[200:203], v[184:187], v[84:87]
	v_mfma_f32_16x16x32_bf16 v[76:79], v[212:215], v[184:187], v[76:79]
	v_mfma_f32_16x16x32_bf16 v[68:71], v[200:203], v[192:195], v[68:71]
	v_mfma_f32_16x16x32_bf16 v[64:67], v[212:215], v[192:195], v[64:67]

	s_mov_b32 m0, s33
	v_lshl_add_u64 v[166:167], v[216:217], 0, s[6:7]
	s_barrier
	ds_read_b128 v[154:157], v160 offset:49152
	ds_read_b128 v[162:165], v160 offset:50176
	ds_read_b128 v[172:175], v160 offset:51200
	ds_read_b128 v[176:179], v160 offset:52224
	ds_read_b128 v[180:183], v160 offset:53248
	ds_read_b128 v[184:187], v160 offset:54272
	ds_read_b128 v[188:191], v160 offset:55296
	ds_read_b128 v[192:195], v160 offset:56320
	global_load_lds_dwordx4 v[166:167], off
	s_mov_b32 m0, s34
	v_lshl_add_u64 v[166:167], v[218:219], 0, s[6:7]

	global_load_lds_dwordx4 v[166:167], off
	s_barrier
	s_waitcnt lgkmcnt(0)


	v_mfma_f32_16x16x32_bf16 v[60:63], v[128:131], v[154:157], v[60:63]
	v_mfma_f32_16x16x32_bf16 v[56:59], v[136:139], v[154:157], v[56:59]
	v_mfma_f32_16x16x32_bf16 v[52:55], v[128:131], v[172:175], v[52:55]
	v_mfma_f32_16x16x32_bf16 v[40:43], v[136:139], v[172:175], v[40:43]
	v_mfma_f32_16x16x32_bf16 v[36:39], v[128:131], v[180:183], v[36:39]
	v_mfma_f32_16x16x32_bf16 v[24:27], v[136:139], v[180:183], v[24:27]
	v_mfma_f32_16x16x32_bf16 v[20:23], v[128:131], v[188:191], v[20:23]
	v_mfma_f32_16x16x32_bf16 v[8:11], v[136:139], v[188:191], v[8:11]
	v_mfma_f32_16x16x32_bf16 v[60:63], v[132:135], v[162:165], v[60:63]
	v_mfma_f32_16x16x32_bf16 v[56:59], v[150:153], v[162:165], v[56:59]
	v_mfma_f32_16x16x32_bf16 v[52:55], v[132:135], v[176:179], v[52:55]
	v_mfma_f32_16x16x32_bf16 v[40:43], v[150:153], v[176:179], v[40:43]
	v_mfma_f32_16x16x32_bf16 v[36:39], v[132:135], v[184:187], v[36:39]
	v_mfma_f32_16x16x32_bf16 v[24:27], v[150:153], v[184:187], v[24:27]
	v_mfma_f32_16x16x32_bf16 v[20:23], v[132:135], v[192:195], v[20:23]
	v_mfma_f32_16x16x32_bf16 v[8:11], v[150:153], v[192:195], v[8:11]

	s_barrier
	s_add_u32 s18, s18, 0x160080
	s_addc_u32 s19, s19, 0
	s_add_i32 s20, s20, s25
	s_mov_b32 m0, s20
	v_lshl_add_u64 v[128:129], s[18:19], 0, v[140:141]

	global_load_lds_dwordx4 v[128:129], off
	s_add_i32 m0, s20, 0x2000
	v_lshl_add_u64 v[128:129], s[18:19], 0, v[142:143]

	global_load_lds_dwordx4 v[128:129], off
	s_waitcnt vmcnt(6)
	s_barrier

	v_mfma_f32_16x16x32_bf16 v[48:51], v[196:199], v[154:157], v[48:51]
	v_mfma_f32_16x16x32_bf16 v[44:47], v[204:207], v[154:157], v[44:47]
	v_mfma_f32_16x16x32_bf16 v[32:35], v[196:199], v[172:175], v[32:35]
	v_mfma_f32_16x16x32_bf16 v[28:31], v[204:207], v[172:175], v[28:31]
	v_mfma_f32_16x16x32_bf16 v[16:19], v[196:199], v[180:183], v[16:19]
	v_mfma_f32_16x16x32_bf16 v[12:15], v[204:207], v[180:183], v[12:15]
	v_mfma_f32_16x16x32_bf16 v[4:7], v[196:199], v[188:191], v[4:7]
	v_mfma_f32_16x16x32_bf16 v[0:3], v[204:207], v[188:191], v[0:3]
	v_mfma_f32_16x16x32_bf16 v[48:51], v[200:203], v[162:165], v[48:51]
	v_mfma_f32_16x16x32_bf16 v[44:47], v[212:215], v[162:165], v[44:47]
	v_mfma_f32_16x16x32_bf16 v[32:35], v[200:203], v[176:179], v[32:35]
	v_mfma_f32_16x16x32_bf16 v[28:31], v[212:215], v[176:179], v[28:31]
	v_mfma_f32_16x16x32_bf16 v[16:19], v[200:203], v[184:187], v[16:19]
	v_mfma_f32_16x16x32_bf16 v[12:15], v[212:215], v[184:187], v[12:15]
	v_mfma_f32_16x16x32_bf16 v[4:7], v[200:203], v[192:195], v[4:7]
	v_mfma_f32_16x16x32_bf16 v[0:3], v[212:215], v[192:195], v[0:3]

	s_add_u32 s16, s16, 0x100
	s_addc_u32 s17, s17, 0
	s_add_u32 s52, s52, 0x100
	s_addc_u32 s53, s53, 0
	s_cmp_ge_i32 s54, s51
	s_mov_b32 s18, s54
	s_barrier
	s_cbranch_scc0 .LBB0_1258
	v_mov_b32_e32 v128, v210
	v_mov_b32_e32 v129, v169
	s_mov_b64 s[16:17], -1
	v_lshl_add_u32 v128, v128, 4, v129
	v_ashrrev_i32_e32 v150, 2, v128
	v_and_b32_e32 v129, 3, v129
	v_and_b32_e32 v128, -4, v128
	v_lshl_add_u32 v162, v129, 6, v128
	s_cmp_lt_i32 s2, 0
	v_lshlrev_b32_e32 v144, 4, v129
	s_cbranch_scc0 .LBB0_1261
	s_lshl_b32 s13, s50, 8
	s_add_i32 s13, s13, s30
	v_add_u32_e32 v128, s13, v150
	v_ashrrev_i32_e32 v129, 31, v128
	v_readlane_b32 s52, v254, 22
	v_lshlrev_b64 v[128:129], 13, v[128:129]
	v_readlane_b32 s66, v254, 36
	v_readlane_b32 s67, v254, 37
	s_lshl_b32 s16, s49, 8
	s_ashr_i32 s17, s16, 31
	v_lshl_add_u64 v[128:129], s[66:67], 0, v[128:129]
	v_lshl_add_u64 v[128:129], s[16:17], 2, v[128:129]
	s_lshl_b32 s16, s31, 2
	s_mov_b32 s17, s3
	v_lshl_add_u64 v[128:129], v[128:129], 0, s[16:17]
	v_lshl_add_u64 v[152:153], v[128:129], 0, v[144:145]
	global_load_dwordx4 v[164:167], v[152:153], off
	global_load_dwordx4 v[172:175], v[152:153], off offset:64
	global_load_dwordx4 v[176:179], v[152:153], off offset:512
	global_load_dwordx4 v[180:183], v[152:153], off offset:576
	v_add_co_u32_e32 v136, vcc, s37, v152
	ds_bpermute_b32 v138, v162, v124
	s_nop 0
	v_addc_co_u32_e32 v137, vcc, 0, v153, vcc
	global_load_dwordx4 v[184:187], v[136:137], off
	global_load_dwordx4 v[188:191], v[136:137], off offset:64
	global_load_dwordx4 v[192:195], v[136:137], off offset:512
	global_load_dwordx4 v[132:135], v[136:137], off offset:576
	v_add_co_u32_e32 v208, vcc, s38, v152
	ds_bpermute_b32 v139, v162, v125
	s_nop 0
	v_addc_co_u32_e32 v209, vcc, 0, v153, vcc
	global_load_dwordx4 v[196:199], v[208:209], off
	global_load_dwordx4 v[200:203], v[208:209], off offset:64
	global_load_dwordx4 v[204:207], v[208:209], off offset:512
	global_load_dwordx4 v[212:215], v[208:209], off offset:576
	v_add_co_u32_e32 v154, vcc, s39, v152
	ds_bpermute_b32 v156, v162, v126
	s_nop 0
	v_addc_co_u32_e32 v155, vcc, 0, v153, vcc
	global_load_dwordx4 v[216:219], v[154:155], off
	global_load_dwordx4 v[220:223], v[154:155], off offset:64
	global_load_dwordx4 v[224:227], v[154:155], off offset:512
	global_load_dwordx4 v[128:131], v[154:155], off offset:576
	ds_bpermute_b32 v157, v162, v127
	ds_bpermute_b32 v228, v162, v120
	ds_bpermute_b32 v229, v162, v121
	ds_bpermute_b32 v230, v162, v122
	ds_bpermute_b32 v231, v162, v123
	ds_bpermute_b32 v232, v162, v112
	ds_bpermute_b32 v233, v162, v113
	ds_bpermute_b32 v234, v162, v114
	ds_bpermute_b32 v235, v162, v115
	ds_bpermute_b32 v236, v162, v108
	ds_bpermute_b32 v237, v162, v109
	ds_bpermute_b32 v238, v162, v110
	ds_bpermute_b32 v239, v162, v111
	ds_bpermute_b32 v240, v162, v116
	ds_bpermute_b32 v241, v162, v117
	ds_bpermute_b32 v242, v162, v118
	ds_bpermute_b32 v243, v162, v119
	ds_bpermute_b32 v244, v162, v104
	ds_bpermute_b32 v245, v162, v105
	ds_bpermute_b32 v246, v162, v106
	ds_bpermute_b32 v247, v162, v107
	ds_bpermute_b32 v248, v162, v100
	ds_bpermute_b32 v249, v162, v101
	ds_bpermute_b32 v250, v162, v102
	ds_bpermute_b32 v251, v162, v103
	ds_bpermute_b32 v252, v162, v94
	ds_bpermute_b32 v253, v162, v95
	v_readlane_b32 s53, v254, 23
	v_readlane_b32 s54, v254, 24
	v_readlane_b32 s55, v254, 25
	v_readlane_b32 s56, v254, 26
	v_readlane_b32 s57, v254, 27
	v_readlane_b32 s58, v254, 28
	v_readlane_b32 s59, v254, 29
	v_readlane_b32 s60, v254, 30
	v_readlane_b32 s61, v254, 31
	v_readlane_b32 s62, v254, 32
	v_readlane_b32 s63, v254, 33
	v_readlane_b32 s64, v254, 34
	v_readlane_b32 s65, v254, 35
	s_mov_b64 s[16:17], 0
	s_waitcnt vmcnt(0) lgkmcnt(0)
	v_pk_add_f32 v[164:165], v[164:165], v[138:139]
	ds_bpermute_b32 v138, v162, v92
	ds_bpermute_b32 v139, v162, v93
	v_pk_add_f32 v[166:167], v[166:167], v[156:157]
	v_pk_add_f32 v[172:173], v[172:173], v[228:229]
	v_pk_add_f32 v[174:175], v[174:175], v[230:231]
	v_pk_add_f32 v[178:179], v[178:179], v[234:235]
	v_pk_add_f32 v[176:177], v[176:177], v[232:233]
	v_pk_add_f32 v[182:183], v[182:183], v[238:239]
	v_pk_add_f32 v[180:181], v[180:181], v[236:237]
	global_store_dwordx4 v[152:153], v[164:167], off
	global_store_dwordx4 v[152:153], v[172:175], off offset:64
	global_store_dwordx4 v[152:153], v[176:179], off offset:512
	global_store_dwordx4 v[152:153], v[180:183], off offset:576
	v_pk_add_f32 v[166:167], v[186:187], v[242:243]
	v_pk_add_f32 v[164:165], v[184:185], v[240:241]
	v_pk_add_f32 v[172:173], v[188:189], v[244:245]
	v_add_co_u32_e32 v156, vcc, s40, v152
	v_pk_add_f32 v[174:175], v[190:191], v[246:247]
	v_pk_add_f32 v[178:179], v[194:195], v[250:251]
	v_pk_add_f32 v[176:177], v[192:193], v[248:249]
	global_store_dwordx4 v[136:137], v[164:167], off
	global_store_dwordx4 v[136:137], v[172:175], off offset:64
	global_store_dwordx4 v[136:137], v[176:179], off offset:512
	v_addc_co_u32_e32 v157, vcc, 0, v153, vcc
	ds_bpermute_b32 v172, v162, v98
	ds_bpermute_b32 v173, v162, v99
	v_pk_add_f32 v[134:135], v[134:135], v[252:253]
	global_load_dwordx4 v[164:167], v[156:157], off
	s_waitcnt lgkmcnt(2)
	v_pk_add_f32 v[132:133], v[132:133], v[138:139]
	global_store_dwordx4 v[136:137], v[132:135], off offset:576
	ds_bpermute_b32 v132, v162, v96
	ds_bpermute_b32 v133, v162, v97
	ds_bpermute_b32 v136, v162, v90
	ds_bpermute_b32 v137, v162, v91
	ds_bpermute_b32 v138, v162, v88
	ds_bpermute_b32 v139, v162, v89
	s_waitcnt lgkmcnt(6)
	v_pk_add_f32 v[134:135], v[198:199], v[172:173]
	global_load_dwordx4 v[172:175], v[156:157], off offset:64
	s_waitcnt lgkmcnt(4)
	v_pk_add_f32 v[132:133], v[196:197], v[132:133]
	global_store_dwordx4 v[208:209], v[132:135], off
	ds_bpermute_b32 v180, v162, v76
	ds_bpermute_b32 v182, v162, v78
	s_waitcnt lgkmcnt(4)
	v_pk_add_f32 v[134:135], v[202:203], v[136:137]
	ds_bpermute_b32 v136, v162, v86
	ds_bpermute_b32 v137, v162, v87
	s_waitcnt lgkmcnt(4)
	v_pk_add_f32 v[132:133], v[200:201], v[138:139]
	ds_bpermute_b32 v138, v162, v84
	ds_bpermute_b32 v139, v162, v85
	global_store_dwordx4 v[208:209], v[132:135], off offset:64
	global_load_dwordx4 v[132:135], v[156:157], off offset:512
	s_waitcnt lgkmcnt(2)
	v_pk_add_f32 v[178:179], v[206:207], v[136:137]
	ds_bpermute_b32 v183, v162, v79
	s_waitcnt lgkmcnt(1)
	v_pk_add_f32 v[176:177], v[204:205], v[138:139]
	global_load_dwordx4 v[136:139], v[156:157], off offset:576
	ds_bpermute_b32 v181, v162, v77
	global_store_dwordx4 v[208:209], v[176:179], off offset:512
	v_add_co_u32_e32 v204, vcc, s41, v152
	s_waitcnt lgkmcnt(1)
	v_pk_add_f32 v[178:179], v[214:215], v[182:183]
	s_waitcnt lgkmcnt(0)
	v_pk_add_f32 v[176:177], v[212:213], v[180:181]
	ds_bpermute_b32 v180, v162, v80
	ds_bpermute_b32 v181, v162, v81
	ds_bpermute_b32 v182, v162, v82
	ds_bpermute_b32 v183, v162, v83
	v_addc_co_u32_e32 v205, vcc, 0, v153, vcc
	global_store_dwordx4 v[208:209], v[176:179], off offset:576
	global_load_dwordx4 v[176:179], v[204:205], off
	s_waitcnt lgkmcnt(0)
	v_pk_add_f32 v[182:183], v[218:219], v[182:183]
	global_load_dwordx4 v[184:187], v[204:205], off offset:64
	v_pk_add_f32 v[180:181], v[216:217], v[180:181]
	ds_bpermute_b32 v188, v162, v74
	ds_bpermute_b32 v189, v162, v75
	global_store_dwordx4 v[154:155], v[180:183], off
	ds_bpermute_b32 v180, v162, v72
	ds_bpermute_b32 v181, v162, v73
	ds_bpermute_b32 v192, v162, v68
	s_waitcnt lgkmcnt(3)
	v_pk_add_f32 v[182:183], v[222:223], v[188:189]
	global_load_dwordx4 v[188:191], v[204:205], off offset:512
	ds_bpermute_b32 v193, v162, v69
	s_waitcnt lgkmcnt(2)
	v_pk_add_f32 v[180:181], v[220:221], v[180:181]
	ds_bpermute_b32 v194, v162, v70
	ds_bpermute_b32 v195, v162, v71
	global_store_dwordx4 v[154:155], v[180:183], off offset:64
	global_load_dwordx4 v[180:183], v[204:205], off offset:576
	ds_bpermute_b32 v200, v162, v64
	ds_bpermute_b32 v196, v162, v66
	ds_bpermute_b32 v197, v162, v67
	ds_bpermute_b32 v201, v162, v65
	v_add_co_u32_e32 v206, vcc, s42, v152
	s_waitcnt lgkmcnt(4)
	v_pk_add_f32 v[194:195], v[226:227], v[194:195]
	v_pk_add_f32 v[192:193], v[224:225], v[192:193]
	v_addc_co_u32_e32 v207, vcc, 0, v153, vcc
	global_store_dwordx4 v[154:155], v[192:195], off offset:512
	global_load_dwordx4 v[192:195], v[206:207], off
	s_waitcnt lgkmcnt(1)
	v_pk_add_f32 v[130:131], v[130:131], v[196:197]
	s_waitcnt lgkmcnt(0)
	v_pk_add_f32 v[128:129], v[128:129], v[200:201]
	global_load_dwordx4 v[196:199], v[206:207], off offset:64
	ds_bpermute_b32 v202, v162, v62
	ds_bpermute_b32 v203, v162, v63
	global_store_dwordx4 v[154:155], v[128:131], off offset:576
	ds_bpermute_b32 v128, v162, v60
	ds_bpermute_b32 v129, v162, v61
	ds_bpermute_b32 v208, v162, v58
	ds_bpermute_b32 v209, v162, v59
	s_waitcnt vmcnt(18) lgkmcnt(4)
	v_pk_add_f32 v[130:131], v[166:167], v[202:203]
	ds_bpermute_b32 v154, v162, v56
	global_load_dwordx4 v[200:203], v[206:207], off offset:512
	ds_bpermute_b32 v155, v162, v57
	s_waitcnt lgkmcnt(4)
	v_pk_add_f32 v[128:129], v[164:165], v[128:129]
	global_load_dwordx4 v[164:167], v[206:207], off offset:576
	ds_bpermute_b32 v212, v162, v44
	global_store_dwordx4 v[156:157], v[128:131], off
	ds_bpermute_b32 v214, v162, v46
	ds_bpermute_b32 v215, v162, v47
	s_waitcnt vmcnt(19) lgkmcnt(5)
	v_pk_add_f32 v[130:131], v[174:175], v[208:209]
	v_add_co_u32_e32 v208, vcc, s43, v152
	s_waitcnt lgkmcnt(3)
	v_pk_add_f32 v[128:129], v[172:173], v[154:155]
	v_addc_co_u32_e32 v209, vcc, 0, v153, vcc
	global_store_dwordx4 v[156:157], v[128:131], off offset:64
	ds_bpermute_b32 v172, v162, v48
	ds_bpermute_b32 v173, v162, v49
	global_load_dwordx4 v[128:131], v[208:209], off
	global_load_dwordx4 v[152:155], v[208:209], off offset:64
	ds_bpermute_b32 v174, v162, v50
	ds_bpermute_b32 v175, v162, v51
	ds_bpermute_b32 v213, v162, v45
	s_waitcnt vmcnt(19) lgkmcnt(3)
	v_pk_add_f32 v[132:133], v[132:133], v[172:173]
	ds_bpermute_b32 v172, v162, v54
	ds_bpermute_b32 v173, v162, v55
	s_waitcnt lgkmcnt(3)
	v_pk_add_f32 v[134:135], v[134:135], v[174:175]
	global_store_dwordx4 v[156:157], v[132:135], off offset:512
	s_waitcnt vmcnt(16) lgkmcnt(0)
	v_pk_add_f32 v[174:175], v[178:179], v[172:173]
	v_pk_add_f32 v[134:135], v[138:139], v[214:215]
	v_pk_add_f32 v[132:133], v[136:137], v[212:213]
	global_store_dwordx4 v[156:157], v[132:135], off offset:576
	global_load_dwordx4 v[132:135], v[208:209], off offset:512
	ds_bpermute_b32 v156, v162, v52
	global_load_dwordx4 v[136:139], v[208:209], off offset:576
	ds_bpermute_b32 v157, v162, v53
	ds_bpermute_b32 v212, v162, v40
	ds_bpermute_b32 v214, v162, v42
	ds_bpermute_b32 v215, v162, v43
	ds_bpermute_b32 v213, v162, v41
	s_waitcnt lgkmcnt(4)
	v_pk_add_f32 v[172:173], v[176:177], v[156:157]
	global_store_dwordx4 v[204:205], v[172:175], off
	ds_bpermute_b32 v156, v162, v32
	ds_bpermute_b32 v157, v162, v33
	s_waitcnt vmcnt(19) lgkmcnt(3)
	v_pk_add_f32 v[174:175], v[186:187], v[214:215]
	s_waitcnt lgkmcnt(2)
	v_pk_add_f32 v[172:173], v[184:185], v[212:213]
	global_store_dwordx4 v[204:205], v[172:175], off offset:64
	ds_bpermute_b32 v172, v162, v34
	ds_bpermute_b32 v173, v162, v35
	ds_bpermute_b32 v176, v162, v28
	ds_bpermute_b32 v178, v162, v30
	ds_bpermute_b32 v179, v162, v31
	ds_bpermute_b32 v177, v162, v29
	s_waitcnt vmcnt(18) lgkmcnt(4)
	v_pk_add_f32 v[174:175], v[190:191], v[172:173]
	v_pk_add_f32 v[172:173], v[188:189], v[156:157]
	global_store_dwordx4 v[204:205], v[172:175], off offset:512
	ds_bpermute_b32 v156, v162, v36
	ds_bpermute_b32 v157, v162, v37
	s_waitcnt vmcnt(17) lgkmcnt(3)
	v_pk_add_f32 v[174:175], v[182:183], v[178:179]
	s_waitcnt lgkmcnt(2)
	v_pk_add_f32 v[172:173], v[180:181], v[176:177]
	global_store_dwordx4 v[204:205], v[172:175], off offset:576
	ds_bpermute_b32 v172, v162, v38
	ds_bpermute_b32 v173, v162, v39
	ds_bpermute_b32 v176, v162, v24
	ds_bpermute_b32 v178, v162, v26
	ds_bpermute_b32 v179, v162, v27
	ds_bpermute_b32 v177, v162, v25
	s_waitcnt vmcnt(16) lgkmcnt(4)
	v_pk_add_f32 v[174:175], v[194:195], v[172:173]
	v_pk_add_f32 v[172:173], v[192:193], v[156:157]
	global_store_dwordx4 v[206:207], v[172:175], off
	ds_bpermute_b32 v156, v162, v16
	ds_bpermute_b32 v157, v162, v17
	s_waitcnt vmcnt(16) lgkmcnt(3)
	v_pk_add_f32 v[174:175], v[198:199], v[178:179]
	s_waitcnt lgkmcnt(2)
	v_pk_add_f32 v[172:173], v[196:197], v[176:177]
	ds_bpermute_b32 v176, v162, v12
	ds_bpermute_b32 v178, v162, v14
	ds_bpermute_b32 v179, v162, v15
	ds_bpermute_b32 v177, v162, v13
	global_store_dwordx4 v[206:207], v[172:175], off offset:64
	ds_bpermute_b32 v172, v162, v18
	ds_bpermute_b32 v173, v162, v19
	s_waitcnt vmcnt(14) lgkmcnt(3)
	v_pk_add_f32 v[166:167], v[166:167], v[178:179]
	s_waitcnt lgkmcnt(2)
	v_pk_add_f32 v[164:165], v[164:165], v[176:177]
	global_store_dwordx4 v[206:207], v[164:167], off offset:576
	ds_bpermute_b32 v164, v162, v22
	s_waitcnt lgkmcnt(1)
	v_pk_add_f32 v[174:175], v[202:203], v[172:173]
	v_pk_add_f32 v[172:173], v[200:201], v[156:157]
	ds_bpermute_b32 v156, v162, v20
	ds_bpermute_b32 v157, v162, v21
	ds_bpermute_b32 v165, v162, v23
	global_store_dwordx4 v[206:207], v[172:175], off offset:512
	ds_bpermute_b32 v166, v162, v8
	ds_bpermute_b32 v172, v162, v10
	ds_bpermute_b32 v173, v162, v11
	ds_bpermute_b32 v167, v162, v9
	s_waitcnt vmcnt(13) lgkmcnt(4)
	v_pk_add_f32 v[130:131], v[130:131], v[164:165]
	v_pk_add_f32 v[128:129], v[128:129], v[156:157]
	global_store_dwordx4 v[208:209], v[128:131], off
	s_waitcnt vmcnt(13) lgkmcnt(1)
	s_nop 0
	v_pk_add_f32 v[130:131], v[154:155], v[172:173]
	s_waitcnt lgkmcnt(0)
	v_pk_add_f32 v[128:129], v[152:153], v[166:167]
	global_store_dwordx4 v[208:209], v[128:131], off offset:64
	ds_bpermute_b32 v128, v162, v4
	ds_bpermute_b32 v129, v162, v5
	ds_bpermute_b32 v130, v162, v6
	ds_bpermute_b32 v131, v162, v7
	ds_bpermute_b32 v152, v162, v0
	ds_bpermute_b32 v154, v162, v2
	ds_bpermute_b32 v155, v162, v3
	ds_bpermute_b32 v153, v162, v1
	s_waitcnt vmcnt(11) lgkmcnt(4)
	v_pk_add_f32 v[130:131], v[134:135], v[130:131]
	v_pk_add_f32 v[128:129], v[132:133], v[128:129]
	global_store_dwordx4 v[208:209], v[128:131], off offset:512
	s_waitcnt vmcnt(11) lgkmcnt(1)
	s_nop 0
	v_pk_add_f32 v[130:131], v[138:139], v[154:155]
	s_waitcnt lgkmcnt(0)
	v_pk_add_f32 v[128:129], v[136:137], v[152:153]
	global_store_dwordx4 v[208:209], v[128:131], off offset:576
